# FFT stage-1 items of the overloaded workgroups moved to others; boundary zeros of the conv shifts written by the DPP op itself
# speedup vs baseline: 1.0420x; 1.0074x over previous
.LBB0_329:
	s_cmp_lt_u32 s62, 16
	s_cbranch_scc1 .LBB0_335
	s_mov_b64 s[0:1], s[60:61]
	v_mbcnt_lo_u32_b32 v0, -1, 0
	v_mbcnt_hi_u32_b32 v0, -1, v0
	s_movk_i32 s2, 0x800
	v_or_b32_e32 v1, s68, v0
	s_load_dwordx2 s[0:1], s[0:1], 0xc0
	v_readfirstlane_b32 s8, v1
	v_cmp_gt_i32_e32 vcc, s2, v1
	s_waitcnt lgkmcnt(0)
	s_and_saveexec_b64 s[2:3], vcc
	s_cbranch_execz .LBB0_332
	s_add_u32 s4, s0, 0x180000
	s_addc_u32 s5, s1, 0
	v_lshlrev_b32_e32 v2, 4, v1
	s_mov_b64 s[6:7], 0

.LBB0_332:
	s_or_b64 exec, exec, s[2:3]
	s_ashr_i32 s5, s8, 6
	s_add_i32 s2, s5, s69
	s_sub_i32 s93, s2, 0x80
	s_cmp_lt_u32 s93, 0x100
	s_cbranch_scc0 .Lf1_a
	s_cmp_lt_u32 s93, 0x80
	s_cselect_b32 s94, 0, 0x780
	s_add_i32 s2, s93, s94
.Lf1_a:
	s_cmpk_gt_i32 s2, 0xfff
	s_waitcnt lgkmcnt(0)
	s_barrier
	s_cbranch_scc1 .LBB0_335
	v_and_b32_e32 v2, 15, v0
	v_lshrrev_b32_e32 v1, 1, v0
	v_and_b32_e32 v3, 48, v0
	v_lshrrev_b32_e32 v0, 2, v0
	s_add_u32 s3, s0, 0x3200000
	v_and_b32_e32 v1, 24, v1
	v_and_b32_e32 v32, 12, v0
	s_addc_u32 s4, s1, 0
	v_mul_u32_u24_e32 v28, 0xa0000, v1
	v_add_u32_e32 v1, 0, v3
	v_mul_u32_u24_e32 v3, 0x110, v2
	v_lshlrev_b32_e32 v33, 1, v32
	s_lshl_b32 s5, s5, 4
	v_readlane_b32 s6, v254, 10
	v_mov_b32_e32 v29, v169
	v_or_b32_e32 v34, 2, v33
	v_or_b32_e32 v35, 4, v33
	v_or_b32_e32 v36, 6, v33
	v_or_b32_e32 v37, 32, v33
	v_or_b32_e32 v38, 34, v33
	v_or_b32_e32 v39, 36, v33
	v_or_b32_e32 v40, 38, v33
	v_or_b32_e32 v41, 64, v33
	v_or_b32_e32 v42, 0x42, v33
	v_or_b32_e32 v43, 0x44, v33
	v_or_b32_e32 v44, 0x46, v33
	v_or_b32_e32 v45, 0x60, v33
	v_or_b32_e32 v46, 0x62, v33
	v_or_b32_e32 v47, 0x64, v33
	v_or_b32_e32 v48, 0x66, v33
	s_add_i32 s5, s6, s5
	v_lshlrev_b32_e32 v168, 1, v2
	v_add_u32_e32 v49, v1, v3
.LBB0_334:
	s_ashr_i32 s7, s2, 11
	s_bfe_u32 s6, s2, 0x70004
	s_lshl_b32 s8, s7, 13
	s_or_b32 s8, s8, s6
	s_mul_hi_i32 s9, s8, 0x1400
	s_mulk_i32 s8, 0x1400
	s_add_u32 s10, s0, s8
	s_addc_u32 s9, s1, s9
	s_and_b32 s8, s5, 0xf0
	s_lshl_b32 s8, s8, 1
	s_add_u32 s10, s10, s8
	s_addc_u32 s11, s9, 0
	v_lshl_add_u64 v[0:1], s[10:11], 0, v[28:29]
	v_lshl_add_u64 v[0:1], v[0:1], 0, v[168:169]
	s_mov_b32 s9, 0x7400000
	v_add_co_u32_e32 v4, vcc, s9, v0
	s_mov_b32 s9, 0x74a0000
	s_nop 0
	v_addc_co_u32_e32 v5, vcc, 0, v1, vcc
	flat_load_ushort v52, v[4:5] offset:2048
	v_add_co_u32_e32 v4, vcc, s9, v0
	s_mov_b32 s9, 0x7540000
	s_nop 0
	v_addc_co_u32_e32 v5, vcc, 0, v1, vcc
	v_add_co_u32_e32 v6, vcc, s9, v0
	s_mov_b32 s9, 0x75e0000
	s_nop 0
	v_addc_co_u32_e32 v7, vcc, 0, v1, vcc
	v_add_co_u32_e32 v8, vcc, s9, v0
	s_mov_b32 s9, 0x7680000
	s_nop 0
	v_addc_co_u32_e32 v9, vcc, 0, v1, vcc
	v_add_co_u32_e32 v10, vcc, s9, v0
	s_mov_b32 s9, 0x7720000
	s_nop 0
	v_addc_co_u32_e32 v11, vcc, 0, v1, vcc
	v_add_co_u32_e32 v12, vcc, s9, v0
	s_mov_b32 s9, 0x77c0000
	s_nop 0
	v_addc_co_u32_e32 v13, vcc, 0, v1, vcc
	v_add_co_u32_e32 v14, vcc, s9, v0
	s_mov_b32 s9, 0x7860000
	s_nop 0
	v_addc_co_u32_e32 v15, vcc, 0, v1, vcc
	v_add_co_u32_e32 v16, vcc, s9, v0
	flat_load_ushort v53, v[4:5] offset:2048
	flat_load_ushort v54, v[6:7] offset:2048
	flat_load_ushort v55, v[8:9] offset:2048
	flat_load_ushort v56, v[10:11] offset:2048
	flat_load_ushort v57, v[12:13] offset:2048
	flat_load_ushort v58, v[14:15] offset:2048
	v_addc_co_u32_e32 v17, vcc, 0, v1, vcc
	flat_load_ushort v59, v[16:17] offset:2048
	s_mov_b32 s9, 0x8800000
	v_add_co_u32_e32 v18, vcc, s9, v0
	s_mov_b32 s9, 0x88a0000
	s_nop 0
	v_addc_co_u32_e32 v19, vcc, 0, v1, vcc
	v_add_co_u32_e32 v20, vcc, s9, v0
	s_mov_b32 s9, 0x8940000
	s_nop 0
	v_addc_co_u32_e32 v21, vcc, 0, v1, vcc
	v_add_co_u32_e32 v22, vcc, s9, v0
	s_mov_b32 s9, 0x89e0000
	s_nop 0
	v_addc_co_u32_e32 v23, vcc, 0, v1, vcc
	v_add_co_u32_e32 v24, vcc, s9, v0
	flat_load_ushort v66, v[18:19] offset:2048
	s_nop 0
	v_addc_co_u32_e32 v25, vcc, 0, v1, vcc
	flat_load_ushort v67, v[20:21] offset:2048
	flat_load_ushort v68, v[22:23] offset:2048
	flat_load_ushort v69, v[24:25] offset:2048
	s_mov_b32 s9, 0x8a80000
	v_add_co_u32_e32 v26, vcc, s9, v0
	s_mov_b32 s9, 0x8b20000
	s_nop 0
	v_addc_co_u32_e32 v27, vcc, 0, v1, vcc
	v_add_co_u32_e32 v30, vcc, s9, v0
	s_mov_b32 s9, 0x8bc0000
	s_nop 0
	v_addc_co_u32_e32 v31, vcc, 0, v1, vcc
	v_add_co_u32_e32 v50, vcc, s9, v0
	flat_load_ushort v70, v[26:27] offset:2048
	flat_load_ushort v71, v[30:31] offset:2048
	v_addc_co_u32_e32 v51, vcc, 0, v1, vcc
	flat_load_ushort v72, v[50:51] offset:2048
	s_mov_b64 s[10:11], 0x7400800
	s_mov_b32 s9, 0x8c60000
	v_lshl_add_u64 v[2:3], v[0:1], 0, s[10:11]
	v_add_co_u32_e32 v0, vcc, s9, v0
	s_lshl_b32 s7, s7, 7
	s_nop 0
	v_addc_co_u32_e32 v1, vcc, 0, v1, vcc
	flat_load_ushort v73, v[0:1] offset:2048
	flat_load_ushort v74, v[2:3] offset:512
	flat_load_ushort v75, v[4:5] offset:2560
	flat_load_ushort v76, v[6:7] offset:2560
	flat_load_ushort v77, v[8:9] offset:2560
	flat_load_ushort v78, v[10:11] offset:2560
	flat_load_ushort v79, v[12:13] offset:2560
	flat_load_ushort v80, v[14:15] offset:2560
	flat_load_ushort v81, v[16:17] offset:2560
	flat_load_ushort v4, v[18:19] offset:2560
	flat_load_ushort v5, v[20:21] offset:2560
	flat_load_ushort v6, v[22:23] offset:2560
	flat_load_ushort v7, v[24:25] offset:2560
	flat_load_ushort v8, v[26:27] offset:2560
	flat_load_ushort v9, v[30:31] offset:2560
	flat_load_ushort v10, v[50:51] offset:2560
	flat_load_ushort v11, v[0:1] offset:2560
	ds_read_b128 v[12:15], v49
	ds_read_b128 v[16:19], v49 offset:4352
	ds_read_b128 v[20:23], v49 offset:8704
	ds_read_b128 v[24:27], v49 offset:13056
	ds_read_b128 v[62:65], v49 offset:30464
	s_lshl_b32 s9, s6, 9
	s_add_u32 s9, s3, s9
	s_addc_u32 s10, s4, 0
	s_add_u32 s8, s9, s8
	s_addc_u32 s9, s10, 0
	v_lshl_add_u64 v[30:31], s[8:9], 0, v[168:169]
	s_mul_i32 s8, s6, 13
	s_add_i32 s2, s2, s70
	s_sub_i32 s93, s2, 0x800
	s_cmp_lt_u32 s93, 0x80
	s_cselect_b32 s94, 1, 0
	s_sub_i32 s93, s2, 0x1000
	s_cmp_lt_u32 s93, 0x80
	s_cselect_b32 s93, 1, 0
	s_or_b32 s93, s93, s94
	s_cbranch_scc0 .Lf1_b
	s_lshr_b32 s2, s68, 6
	s_add_i32 s2, s2, s69
.Lf1_b:
	s_add_i32 s5, s5, s81
	s_cmpk_lt_i32 s2, 0x1000
	s_waitcnt vmcnt(0) lgkmcnt(0)
	v_perm_b32 v0, v53, v52, s89
	ds_read_b128 v[50:53], v49 offset:17408
	v_perm_b32 v1, v55, v54, s89
	v_perm_b32 v2, v57, v56, s89
	ds_read_b128 v[54:57], v49 offset:21760
	v_perm_b32 v3, v59, v58, s89
	ds_read_b128 v[58:61], v49 offset:26112
	s_nop 0
	v_mfma_f32_16x16x32_bf16 v[12:15], v[12:15], v[0:3], 0
	v_mfma_f32_16x16x32_bf16 v[16:19], v[16:19], v[0:3], 0
	v_mfma_f32_16x16x32_bf16 v[20:23], v[20:23], v[0:3], 0
	v_mfma_f32_16x16x32_bf16 v[24:27], v[24:27], v[0:3], 0
	s_waitcnt lgkmcnt(2)
	v_mfma_f32_16x16x32_bf16 v[50:53], v[50:53], v[0:3], 0
	s_waitcnt lgkmcnt(1)
	v_mfma_f32_16x16x32_bf16 v[54:57], v[54:57], v[0:3], 0
	s_waitcnt lgkmcnt(0)
	v_mfma_f32_16x16x32_bf16 v[58:61], v[58:61], v[0:3], 0
	v_mfma_f32_16x16x32_bf16 v[0:3], v[62:65], v[0:3], 0
	v_perm_b32 v63, v69, v68, s89
	v_perm_b32 v62, v67, v66, s89
	ds_read_b128 v[66:69], v49 offset:64
	v_perm_b32 v64, v71, v70, s89
	v_perm_b32 v65, v73, v72, s89
	v_perm_b32 v70, v5, v4, s89
	v_perm_b32 v71, v7, v6, s89
	ds_read_b128 v[4:7], v49 offset:17600
	s_waitcnt lgkmcnt(1)
	v_mfma_f32_16x16x32_bf16 v[12:15], v[66:69], v[62:65], v[12:15]
	ds_read_b128 v[66:69], v49 offset:4416
	v_perm_b32 v73, v11, v10, s89
	v_perm_b32 v72, v9, v8, s89
	s_waitcnt lgkmcnt(0)
	v_mfma_f32_16x16x32_bf16 v[16:19], v[66:69], v[62:65], v[16:19]
	ds_read_b128 v[66:69], v49 offset:8768
	s_waitcnt lgkmcnt(0)
	v_mfma_f32_16x16x32_bf16 v[20:23], v[66:69], v[62:65], v[20:23]
	ds_read_b128 v[66:69], v49 offset:13120
	s_waitcnt lgkmcnt(0)
	v_mfma_f32_16x16x32_bf16 v[24:27], v[66:69], v[62:65], v[24:27]
	ds_read_b128 v[66:69], v49 offset:17472
	s_waitcnt lgkmcnt(0)
	v_mfma_f32_16x16x32_bf16 v[50:53], v[66:69], v[62:65], v[50:53]
	ds_read_b128 v[66:69], v49 offset:21824
	s_waitcnt lgkmcnt(0)
	v_mfma_f32_16x16x32_bf16 v[54:57], v[66:69], v[62:65], v[54:57]
	ds_read_b128 v[66:69], v49 offset:26176
	s_waitcnt lgkmcnt(0)
	v_mfma_f32_16x16x32_bf16 v[58:61], v[66:69], v[62:65], v[58:61]
	ds_read_b128 v[66:69], v49 offset:30528
	s_waitcnt lgkmcnt(0)
	v_mfma_f32_16x16x32_bf16 v[0:3], v[66:69], v[62:65], v[0:3]
	ds_read_b128 v[66:69], v49 offset:128
	v_perm_b32 v65, v81, v80, s89
	v_perm_b32 v64, v79, v78, s89
	v_perm_b32 v63, v77, v76, s89
	v_perm_b32 v62, v75, v74, s89
	s_waitcnt lgkmcnt(0)
	s_nop 0
	v_mfma_f32_16x16x32_bf16 v[12:15], v[66:69], v[62:65], v[12:15]
	ds_read_b128 v[66:69], v49 offset:4480
	s_waitcnt lgkmcnt(0)
	v_mfma_f32_16x16x32_bf16 v[16:19], v[66:69], v[62:65], v[16:19]
	ds_read_b128 v[66:69], v49 offset:8832
	s_waitcnt lgkmcnt(0)
	v_mfma_f32_16x16x32_bf16 v[20:23], v[66:69], v[62:65], v[20:23]
	ds_read_b128 v[66:69], v49 offset:13184
	s_waitcnt lgkmcnt(0)
	v_mfma_f32_16x16x32_bf16 v[66:69], v[66:69], v[62:65], v[24:27]
	s_nop 2
	ds_read_b128 v[24:27], v49 offset:17536
	s_waitcnt lgkmcnt(0)
	v_mfma_f32_16x16x32_bf16 v[50:53], v[24:27], v[62:65], v[50:53]
	ds_read_b128 v[24:27], v49 offset:21888
	s_waitcnt lgkmcnt(0)
	v_mfma_f32_16x16x32_bf16 v[54:57], v[24:27], v[62:65], v[54:57]
	ds_read_b128 v[24:27], v49 offset:26240
	s_waitcnt lgkmcnt(0)
	v_mfma_f32_16x16x32_bf16 v[58:61], v[24:27], v[62:65], v[58:61]
	ds_read_b128 v[24:27], v49 offset:30592
	s_waitcnt lgkmcnt(0)
	v_mfma_f32_16x16x32_bf16 v[62:65], v[24:27], v[62:65], v[0:3]
	s_nop 2
	ds_read_b128 v[0:3], v49 offset:192
	v_mfma_f32_16x16x32_bf16 v[50:53], v[4:7], v[70:73], v[50:53]
	ds_read_b128 v[4:7], v49 offset:21952
	s_waitcnt lgkmcnt(1)
	v_mfma_f32_16x16x32_bf16 v[24:27], v[0:3], v[70:73], v[12:15]
	ds_read_b128 v[0:3], v49 offset:4544
	s_waitcnt lgkmcnt(0)
	v_mfma_f32_16x16x32_bf16 v[16:19], v[0:3], v[70:73], v[16:19]
	ds_read_b128 v[0:3], v49 offset:8896
	s_waitcnt lgkmcnt(0)
	v_mfma_f32_16x16x32_bf16 v[8:11], v[0:3], v[70:73], v[20:23]
	ds_read_b128 v[0:3], v49 offset:13248
	v_mfma_f32_16x16x32_bf16 v[20:23], v[4:7], v[70:73], v[54:57]
	ds_read_b128 v[4:7], v49 offset:26304
	s_nop 1
	v_mul_u32_u24_e32 v54, s6, v32
	v_cvt_f32_u32_e32 v54, v54
	s_waitcnt lgkmcnt(0)
	v_mfma_f32_16x16x32_bf16 v[12:15], v[4:7], v[70:73], v[58:61]
	v_mul_f32_e32 v54, 0x39000000, v54
	v_cos_f32_e32 v55, v54
	v_sin_f32_e32 v54, v54
	ds_read_b128 v[4:7], v49 offset:30656
	s_waitcnt lgkmcnt(0)
	v_mfma_f32_16x16x32_bf16 v[4:7], v[4:7], v[70:73], v[62:65]
	v_mul_f32_e32 v56, v54, v50
	v_fmac_f32_e32 v56, v55, v24
	v_mul_f32_e32 v24, v54, v24
	v_or_b32_e32 v54, s7, v33
	v_fma_f32 v24, v55, v50, -v24
	v_ashrrev_i32_e32 v55, 31, v54
	v_lshlrev_b64 v[54:55], 16, v[54:55]
	v_bfe_u32 v50, v56, 16, 1
	v_lshl_add_u64 v[54:55], v[30:31], 0, v[54:55]
	v_add3_u32 v50, v56, v50, s77
	flat_store_short_d16_hi v[54:55], v50
	v_bfe_u32 v50, v24, 16, 1
	v_add_co_u32_e32 v54, vcc, s49, v54
	v_add3_u32 v24, v24, v50, s77
	s_nop 0
	v_addc_co_u32_e32 v55, vcc, 0, v55, vcc
	v_mad_u32_u24 v50, s6, v32, s6
	flat_store_short_d16_hi v[54:55], v24
	v_cvt_f32_u32_e32 v24, v50
	v_add_u32_e32 v50, s6, v50
	v_mfma_f32_16x16x32_bf16 v[0:3], v[0:3], v[70:73], v[66:69]
	v_mul_f32_e32 v24, 0x39000000, v24
	v_cos_f32_e32 v54, v24
	v_sin_f32_e32 v24, v24
	s_nop 0
	v_mul_f32_e32 v55, v24, v51
	v_mul_f32_e32 v24, v24, v25
	v_fma_f32 v51, v54, v51, -v24
	v_or_b32_e32 v24, s7, v34
	v_fmac_f32_e32 v55, v54, v25
	v_ashrrev_i32_e32 v25, 31, v24
	v_lshlrev_b64 v[24:25], 16, v[24:25]
	v_bfe_u32 v54, v55, 16, 1
	v_lshl_add_u64 v[24:25], v[30:31], 0, v[24:25]
	v_add3_u32 v54, v55, v54, s77
	flat_store_short_d16_hi v[24:25], v54
	v_bfe_u32 v54, v51, 16, 1
	v_add_co_u32_e32 v24, vcc, s49, v24
	v_add3_u32 v51, v51, v54, s77
	s_nop 0
	v_addc_co_u32_e32 v25, vcc, 0, v25, vcc
	flat_store_short_d16_hi v[24:25], v51
	v_cvt_f32_u32_e32 v24, v50
	v_mul_f32_e32 v24, 0x39000000, v24
	v_cos_f32_e32 v25, v24
	v_sin_f32_e32 v24, v24
	s_nop 0
	v_mul_f32_e32 v51, v24, v52
	v_mul_f32_e32 v24, v24, v26
	v_fmac_f32_e32 v51, v25, v26
	v_fma_f32 v26, v25, v52, -v24
	v_or_b32_e32 v24, s7, v35
	v_ashrrev_i32_e32 v25, 31, v24
	v_lshlrev_b64 v[24:25], 16, v[24:25]
	v_bfe_u32 v52, v51, 16, 1
	v_lshl_add_u64 v[24:25], v[30:31], 0, v[24:25]
	v_add3_u32 v51, v51, v52, s77
	flat_store_short_d16_hi v[24:25], v51
	v_bfe_u32 v51, v26, 16, 1
	v_add_co_u32_e32 v24, vcc, s49, v24
	v_add3_u32 v26, v26, v51, s77
	s_nop 0
	v_addc_co_u32_e32 v25, vcc, 0, v25, vcc
	flat_store_short_d16_hi v[24:25], v26
	v_add_u32_e32 v26, s6, v50
	v_cvt_f32_u32_e32 v24, v26
	v_add_u32_e32 v26, s8, v26
	v_mul_f32_e32 v24, 0x39000000, v24
	v_cos_f32_e32 v25, v24
	v_sin_f32_e32 v24, v24
	s_nop 0
	v_mul_f32_e32 v50, v24, v53
	v_mul_f32_e32 v24, v24, v27
	v_fmac_f32_e32 v50, v25, v27
	v_fma_f32 v27, v25, v53, -v24
	v_or_b32_e32 v24, s7, v36
	v_ashrrev_i32_e32 v25, 31, v24
	v_lshlrev_b64 v[24:25], 16, v[24:25]
	v_bfe_u32 v51, v50, 16, 1
	v_lshl_add_u64 v[24:25], v[30:31], 0, v[24:25]
	v_add3_u32 v50, v50, v51, s77
	flat_store_short_d16_hi v[24:25], v50
	v_bfe_u32 v50, v27, 16, 1
	v_add_co_u32_e32 v24, vcc, s49, v24
	v_add3_u32 v27, v27, v50, s77
	s_nop 0
	v_addc_co_u32_e32 v25, vcc, 0, v25, vcc
	flat_store_short_d16_hi v[24:25], v27
	v_cvt_f32_u32_e32 v24, v26
	v_mul_f32_e32 v24, 0x39000000, v24
	v_cos_f32_e32 v25, v24
	v_sin_f32_e32 v24, v24
	s_nop 0
	v_mul_f32_e32 v27, v24, v20
	v_fmac_f32_e32 v27, v25, v16
	v_mul_f32_e32 v16, v24, v16
	v_or_b32_e32 v24, s7, v37
	v_fma_f32 v16, v25, v20, -v16
	v_ashrrev_i32_e32 v25, 31, v24
	v_lshlrev_b64 v[24:25], 16, v[24:25]
	v_bfe_u32 v20, v27, 16, 1
	v_lshl_add_u64 v[24:25], v[30:31], 0, v[24:25]
	v_add3_u32 v20, v27, v20, s77
	flat_store_short_d16_hi v[24:25], v20
	v_bfe_u32 v20, v16, 16, 1
	v_add_co_u32_e32 v24, vcc, s49, v24
	v_add3_u32 v16, v16, v20, s77
	s_nop 0
	v_addc_co_u32_e32 v25, vcc, 0, v25, vcc
	v_add_u32_e32 v20, s6, v26
	flat_store_short_d16_hi v[24:25], v16
	v_cvt_f32_u32_e32 v16, v20
	v_add_u32_e32 v20, s6, v20
	v_mul_f32_e32 v16, 0x39000000, v16
	v_cos_f32_e32 v24, v16
	v_sin_f32_e32 v16, v16
	s_nop 0
	v_mul_f32_e32 v25, v16, v21
	v_mul_f32_e32 v16, v16, v17
	v_fma_f32 v21, v24, v21, -v16
	v_or_b32_e32 v16, s7, v38
	v_fmac_f32_e32 v25, v24, v17
	v_ashrrev_i32_e32 v17, 31, v16
	v_lshlrev_b64 v[16:17], 16, v[16:17]
	v_bfe_u32 v24, v25, 16, 1
	v_lshl_add_u64 v[16:17], v[30:31], 0, v[16:17]
	v_add3_u32 v24, v25, v24, s77
	flat_store_short_d16_hi v[16:17], v24
	v_bfe_u32 v24, v21, 16, 1
	v_add_co_u32_e32 v16, vcc, s49, v16
	v_add3_u32 v21, v21, v24, s77
	s_nop 0
	v_addc_co_u32_e32 v17, vcc, 0, v17, vcc
	flat_store_short_d16_hi v[16:17], v21
	v_cvt_f32_u32_e32 v16, v20
	v_mul_f32_e32 v16, 0x39000000, v16
	v_cos_f32_e32 v17, v16
	v_sin_f32_e32 v16, v16
	s_nop 0
	v_mul_f32_e32 v21, v16, v22
	v_mul_f32_e32 v16, v16, v18
	v_fmac_f32_e32 v21, v17, v18
	v_fma_f32 v18, v17, v22, -v16
	v_or_b32_e32 v16, s7, v39
	v_ashrrev_i32_e32 v17, 31, v16
	v_lshlrev_b64 v[16:17], 16, v[16:17]
	v_bfe_u32 v22, v21, 16, 1
	v_lshl_add_u64 v[16:17], v[30:31], 0, v[16:17]
	v_add3_u32 v21, v21, v22, s77
	flat_store_short_d16_hi v[16:17], v21
	v_bfe_u32 v21, v18, 16, 1
	v_add_co_u32_e32 v16, vcc, s49, v16
	v_add3_u32 v18, v18, v21, s77
	s_nop 0
	v_addc_co_u32_e32 v17, vcc, 0, v17, vcc
	flat_store_short_d16_hi v[16:17], v18
	v_add_u32_e32 v18, s6, v20
	v_cvt_f32_u32_e32 v16, v18
	v_add_u32_e32 v18, s8, v18
	v_mul_f32_e32 v16, 0x39000000, v16
	v_cos_f32_e32 v17, v16
	v_sin_f32_e32 v16, v16
	s_nop 0
	v_mul_f32_e32 v20, v16, v23
	v_mul_f32_e32 v16, v16, v19
	v_fmac_f32_e32 v20, v17, v19
	v_fma_f32 v19, v17, v23, -v16
	v_or_b32_e32 v16, s7, v40
	v_ashrrev_i32_e32 v17, 31, v16
	v_lshlrev_b64 v[16:17], 16, v[16:17]
	v_bfe_u32 v21, v20, 16, 1
	v_lshl_add_u64 v[16:17], v[30:31], 0, v[16:17]
	v_add3_u32 v20, v20, v21, s77
	flat_store_short_d16_hi v[16:17], v20
	v_bfe_u32 v20, v19, 16, 1
	v_add_co_u32_e32 v16, vcc, s49, v16
	v_add3_u32 v19, v19, v20, s77
	s_nop 0
	v_addc_co_u32_e32 v17, vcc, 0, v17, vcc
	flat_store_short_d16_hi v[16:17], v19
	v_cvt_f32_u32_e32 v16, v18
	v_mul_f32_e32 v16, 0x39000000, v16
	v_cos_f32_e32 v17, v16
	v_sin_f32_e32 v16, v16
	s_nop 0
	v_mul_f32_e32 v19, v16, v12
	v_fmac_f32_e32 v19, v17, v8
	v_mul_f32_e32 v8, v16, v8
	v_or_b32_e32 v16, s7, v41
	v_fma_f32 v8, v17, v12, -v8
	v_ashrrev_i32_e32 v17, 31, v16
	v_lshlrev_b64 v[16:17], 16, v[16:17]
	v_bfe_u32 v12, v19, 16, 1
	v_lshl_add_u64 v[16:17], v[30:31], 0, v[16:17]
	v_add3_u32 v12, v19, v12, s77
	flat_store_short_d16_hi v[16:17], v12
	v_bfe_u32 v12, v8, 16, 1
	v_add_co_u32_e32 v16, vcc, s49, v16
	v_add3_u32 v8, v8, v12, s77
	s_nop 0
	v_addc_co_u32_e32 v17, vcc, 0, v17, vcc
	v_add_u32_e32 v12, s6, v18
	flat_store_short_d16_hi v[16:17], v8
	v_cvt_f32_u32_e32 v8, v12
	v_add_u32_e32 v12, s6, v12
	v_mul_f32_e32 v8, 0x39000000, v8
	v_cos_f32_e32 v16, v8
	v_sin_f32_e32 v8, v8
	s_nop 0
	v_mul_f32_e32 v17, v8, v13
	v_mul_f32_e32 v8, v8, v9
	v_fma_f32 v13, v16, v13, -v8
	v_or_b32_e32 v8, s7, v42
	v_fmac_f32_e32 v17, v16, v9
	v_ashrrev_i32_e32 v9, 31, v8
	v_lshlrev_b64 v[8:9], 16, v[8:9]
	v_bfe_u32 v16, v17, 16, 1
	v_lshl_add_u64 v[8:9], v[30:31], 0, v[8:9]
	v_add3_u32 v16, v17, v16, s77
	flat_store_short_d16_hi v[8:9], v16
	v_bfe_u32 v16, v13, 16, 1
	v_add_co_u32_e32 v8, vcc, s49, v8
	v_add3_u32 v13, v13, v16, s77
	s_nop 0
	v_addc_co_u32_e32 v9, vcc, 0, v9, vcc
	flat_store_short_d16_hi v[8:9], v13
	v_cvt_f32_u32_e32 v8, v12
	v_mul_f32_e32 v8, 0x39000000, v8
	v_cos_f32_e32 v9, v8
	v_sin_f32_e32 v8, v8
	s_nop 0
	v_mul_f32_e32 v13, v8, v14
	v_mul_f32_e32 v8, v8, v10
	v_fmac_f32_e32 v13, v9, v10
	v_fma_f32 v10, v9, v14, -v8
	v_or_b32_e32 v8, s7, v43
	v_ashrrev_i32_e32 v9, 31, v8
	v_lshlrev_b64 v[8:9], 16, v[8:9]
	v_bfe_u32 v14, v13, 16, 1
	v_lshl_add_u64 v[8:9], v[30:31], 0, v[8:9]
	v_add3_u32 v13, v13, v14, s77
	flat_store_short_d16_hi v[8:9], v13
	v_bfe_u32 v13, v10, 16, 1
	v_add_co_u32_e32 v8, vcc, s49, v8
	v_add3_u32 v10, v10, v13, s77
	s_nop 0
	v_addc_co_u32_e32 v9, vcc, 0, v9, vcc
	flat_store_short_d16_hi v[8:9], v10
	v_add_u32_e32 v10, s6, v12
	v_cvt_f32_u32_e32 v8, v10
	v_add_u32_e32 v10, s8, v10
	v_mul_f32_e32 v8, 0x39000000, v8
	v_cos_f32_e32 v9, v8
	v_sin_f32_e32 v8, v8
	s_nop 0
	v_mul_f32_e32 v12, v8, v15
	v_mul_f32_e32 v8, v8, v11
	v_fmac_f32_e32 v12, v9, v11
	v_fma_f32 v11, v9, v15, -v8
	v_or_b32_e32 v8, s7, v44
	v_ashrrev_i32_e32 v9, 31, v8
	v_lshlrev_b64 v[8:9], 16, v[8:9]
	v_bfe_u32 v13, v12, 16, 1
	v_lshl_add_u64 v[8:9], v[30:31], 0, v[8:9]
	v_add3_u32 v12, v12, v13, s77
	flat_store_short_d16_hi v[8:9], v12
	v_bfe_u32 v12, v11, 16, 1
	v_add_co_u32_e32 v8, vcc, s49, v8
	v_add3_u32 v11, v11, v12, s77
	s_nop 0
	v_addc_co_u32_e32 v9, vcc, 0, v9, vcc
	flat_store_short_d16_hi v[8:9], v11
	v_cvt_f32_u32_e32 v8, v10
	v_mul_f32_e32 v8, 0x39000000, v8
	v_cos_f32_e32 v9, v8
	v_sin_f32_e32 v8, v8
	s_nop 0
	v_mul_f32_e32 v11, v8, v4
	v_fmac_f32_e32 v11, v9, v0
	v_mul_f32_e32 v0, v8, v0
	v_or_b32_e32 v8, s7, v45
	v_fma_f32 v0, v9, v4, -v0
	v_ashrrev_i32_e32 v9, 31, v8
	v_lshlrev_b64 v[8:9], 16, v[8:9]
	v_bfe_u32 v4, v11, 16, 1
	v_lshl_add_u64 v[8:9], v[30:31], 0, v[8:9]
	v_add3_u32 v4, v11, v4, s77
	flat_store_short_d16_hi v[8:9], v4
	v_bfe_u32 v4, v0, 16, 1
	v_add_co_u32_e32 v8, vcc, s49, v8
	v_add3_u32 v0, v0, v4, s77
	s_nop 0
	v_addc_co_u32_e32 v9, vcc, 0, v9, vcc
	v_add_u32_e32 v4, s6, v10
	flat_store_short_d16_hi v[8:9], v0
	v_cvt_f32_u32_e32 v0, v4
	v_add_u32_e32 v4, s6, v4
	v_mul_f32_e32 v0, 0x39000000, v0
	v_cos_f32_e32 v8, v0
	v_sin_f32_e32 v0, v0
	s_nop 0
	v_mul_f32_e32 v9, v0, v5
	v_mul_f32_e32 v0, v0, v1
	v_fma_f32 v5, v8, v5, -v0
	v_or_b32_e32 v0, s7, v46
	v_fmac_f32_e32 v9, v8, v1
	v_ashrrev_i32_e32 v1, 31, v0
	v_lshlrev_b64 v[0:1], 16, v[0:1]
	v_bfe_u32 v8, v9, 16, 1
	v_lshl_add_u64 v[0:1], v[30:31], 0, v[0:1]
	v_add3_u32 v8, v9, v8, s77
	flat_store_short_d16_hi v[0:1], v8
	v_bfe_u32 v8, v5, 16, 1
	v_add_co_u32_e32 v0, vcc, s49, v0
	v_add3_u32 v5, v5, v8, s77
	s_nop 0
	v_addc_co_u32_e32 v1, vcc, 0, v1, vcc
	flat_store_short_d16_hi v[0:1], v5
	v_cvt_f32_u32_e32 v0, v4
	v_mul_f32_e32 v0, 0x39000000, v0
	v_cos_f32_e32 v1, v0
	v_sin_f32_e32 v0, v0
	s_nop 0
	v_mul_f32_e32 v5, v0, v6
	v_mul_f32_e32 v0, v0, v2
	v_fmac_f32_e32 v5, v1, v2
	v_fma_f32 v2, v1, v6, -v0
	v_or_b32_e32 v0, s7, v47
	v_ashrrev_i32_e32 v1, 31, v0
	v_lshlrev_b64 v[0:1], 16, v[0:1]
	v_bfe_u32 v6, v5, 16, 1
	v_lshl_add_u64 v[0:1], v[30:31], 0, v[0:1]
	v_add3_u32 v5, v5, v6, s77
	flat_store_short_d16_hi v[0:1], v5
	v_bfe_u32 v5, v2, 16, 1
	v_add_co_u32_e32 v0, vcc, s49, v0
	v_add3_u32 v2, v2, v5, s77
	s_nop 0
	v_addc_co_u32_e32 v1, vcc, 0, v1, vcc
	flat_store_short_d16_hi v[0:1], v2
	v_add_u32_e32 v0, s6, v4
	v_cvt_f32_u32_e32 v0, v0
	v_mul_f32_e32 v0, 0x39000000, v0
	v_cos_f32_e32 v1, v0
	v_sin_f32_e32 v0, v0
	s_nop 0
	v_mul_f32_e32 v2, v0, v7
	v_mul_f32_e32 v0, v0, v3
	v_fmac_f32_e32 v2, v1, v3
	v_fma_f32 v3, v1, v7, -v0
	v_or_b32_e32 v0, s7, v48
	v_ashrrev_i32_e32 v1, 31, v0
	v_lshlrev_b64 v[0:1], 16, v[0:1]
	v_bfe_u32 v4, v2, 16, 1
	v_lshl_add_u64 v[0:1], v[30:31], 0, v[0:1]
	v_add3_u32 v2, v2, v4, s77
	flat_store_short_d16_hi v[0:1], v2
	v_bfe_u32 v2, v3, 16, 1
	v_add_co_u32_e32 v0, vcc, 0x10000, v0
	v_add3_u32 v2, v3, v2, s77
	s_nop 0
	v_addc_co_u32_e32 v1, vcc, 0, v1, vcc
	flat_store_short_d16_hi v[0:1], v2
	s_cbranch_scc1 .LBB0_334

.LBB0_782:
	v_lshl_or_b32 v184, s44, 7, v192
	v_ashrrev_i32_e32 v185, 31, v184
	v_lshlrev_b64 v[116:117], 2, v[184:185]
	v_lshl_add_u64 v[182:183], s[0:1], 0, v[116:117]
	v_lshl_add_u64 v[180:181], s[12:13], 0, v[116:117]
	v_lshl_add_u64 v[178:179], s[14:15], 0, v[116:117]
	v_lshl_add_u64 v[176:177], s[2:3], 0, v[116:117]
	global_load_dwordx4 v[140:143], v[182:183], off offset:16
	global_load_dwordx4 v[156:159], v[182:183], off
	global_load_dwordx4 v[116:119], v[180:181], off offset:16
	global_load_dwordx4 v[144:147], v[180:181], off
	global_load_dwordx4 v[120:123], v[178:179], off offset:16
	global_load_dwordx4 v[148:151], v[178:179], off
	global_load_dwordx4 v[124:127], v[176:177], off offset:16
	global_load_dwordx4 v[152:155], v[176:177], off
	v_mov_b32_dpp v187, v132 row_ror:15 row_mask:0xf bank_mask:0xf
	v_mov_b32_dpp v186, v136 row_shr:1 row_mask:0xf bank_mask:0xf bound_ctrl:1
	v_mov_b32_dpp v170, v136 row_ror:1 row_mask:0xf bank_mask:0xf
	v_mov_b32_dpp v187, v136 row_shl:1 row_mask:0xf bank_mask:0xf
	s_nop 0
	v_mov_b32_dpp v170, v132 row_shr:1 row_mask:0xf bank_mask:0xf
	v_mov_b32_dpp v171, v112 row_ror:15 row_mask:0xf bank_mask:0xf
	v_mov_b32_dpp v172, v132 row_ror:1 row_mask:0xf bank_mask:0xf
	s_nop 0
	v_mov_b32_dpp v171, v132 row_shl:1 row_mask:0xf bank_mask:0xf
	v_mov_b32_dpp v173, v104 row_ror:15 row_mask:0xf bank_mask:0xf
	v_mov_b32_dpp v172, v112 row_shr:1 row_mask:0xf bank_mask:0xf
	s_nop 0
	v_mov_b32_dpp v173, v112 row_shl:1 row_mask:0xf bank_mask:0xf
	v_mov_b32_dpp v188, v112 row_ror:1 row_mask:0xf bank_mask:0xf
	v_lshl_add_u32 v194, s45, 8, v190
	v_mov_b32_dpp v189, v104 row_shl:1 row_mask:0xf bank_mask:0xf bound_ctrl:1
	v_mov_b32_dpp v188, v104 row_shr:1 row_mask:0xf bank_mask:0xf
	s_movk_i32 s17, 0xb00
	v_readlane_b32 s24, v253, 0
	v_readlane_b32 s25, v253, 1
	v_readlane_b32 s26, v253, 2
	v_readlane_b32 s27, v253, 3
	s_andn2_b64 vcc, exec, s[6:7]
	s_waitcnt vmcnt(0)
	v_mov_b32_e32 v196, v156
	v_mov_b32_e32 v197, v148
	v_pk_mul_f32 v[186:187], v[196:197], v[186:187]
	v_pk_mul_f32 v[170:171], v[196:197], v[170:171]
	v_fma_f32 v136, v136, v144, v186
	v_add_f32_e32 v136, v136, v187
	v_add_f32_e32 v136, v152, v136
	v_mul_f32_e32 v148, 0xbfb8aa3b, v136
	v_exp_f32_e32 v148, v148
	v_fma_f32 v132, v132, v144, v170
	v_add_f32_e32 v132, v132, v171
	v_add_f32_e32 v132, v152, v132
	v_add_f32_e32 v148, 1.0, v148
	v_rcp_f32_e32 v148, v148
	v_pk_mul_f32 v[170:171], v[196:197], v[172:173]
	v_fma_f32 v112, v112, v144, v170
	v_mul_f32_e32 v136, v136, v148
	v_mul_f32_e32 v128, v128, v136
	v_mul_f32_e32 v136, 0xbfb8aa3b, v132
	v_exp_f32_e32 v136, v136
	v_add_f32_e32 v112, v112, v171
	v_add_f32_e32 v112, v152, v112
	v_pk_mul_f32 v[170:171], v[196:197], v[188:189]
	v_add_f32_e32 v136, 1.0, v136
	v_rcp_f32_e32 v136, v136
	v_mov_b32_e32 v148, v157
	v_mul_f32_e32 v132, v132, v136
	v_mul_f32_e32 v108, v108, v132
	v_mul_f32_e32 v132, 0xbfb8aa3b, v112
	v_exp_f32_e32 v132, v132
	v_mov_b32_dpp v188, v137 row_ror:1 row_mask:0xf bank_mask:0xf
	v_mov_b32_dpp v189, v113 row_ror:15 row_mask:0xf bank_mask:0xf
	v_add_f32_e32 v132, 1.0, v132
	v_rcp_f32_e32 v132, v132
	v_mov_b32_dpp v188, v133 row_shr:1 row_mask:0xf bank_mask:0xf
	v_mov_b32_dpp v189, v133 row_shl:1 row_mask:0xf bank_mask:0xf
	v_mov_b32_dpp v186, v133 row_ror:1 row_mask:0xf bank_mask:0xf
	v_mul_f32_e32 v112, v112, v132
	v_mul_f32_e32 v112, v100, v112
	v_fma_f32 v100, v104, v144, v170
	v_add_f32_e32 v100, v100, v171
	v_add_f32_e32 v100, v152, v100
	v_mul_f32_e32 v104, 0xbfb8aa3b, v100
	v_exp_f32_e32 v104, v104
	v_mov_b32_dpp v187, v105 row_ror:15 row_mask:0xf bank_mask:0xf
	v_add_f32_e32 v104, 1.0, v104
	v_rcp_f32_e32 v104, v104
	v_mov_b32_dpp v171, v133 row_ror:15 row_mask:0xf bank_mask:0xf
	v_mov_b32_dpp v170, v137 row_shr:1 row_mask:0xf bank_mask:0xf bound_ctrl:1
	v_mov_b32_dpp v186, v113 row_shr:1 row_mask:0xf bank_mask:0xf
	v_mov_b32_dpp v171, v137 row_shl:1 row_mask:0xf bank_mask:0xf
	v_pk_mul_f32 v[156:157], v[148:149], v[170:171]
	v_mul_f32_e32 v100, v100, v104
	v_fma_f32 v104, v137, v145, v156
	v_add_f32_e32 v104, v104, v157
	v_add_f32_e32 v104, v153, v104
	v_mul_f32_e32 v132, 0xbfb8aa3b, v104
	v_exp_f32_e32 v132, v132
	v_pk_mul_f32 v[136:137], v[148:149], v[188:189]
	v_mov_b32_dpp v187, v113 row_shl:1 row_mask:0xf bank_mask:0xf
	v_mul_f32_e32 v96, v96, v100
	v_add_f32_e32 v132, 1.0, v132
	v_rcp_f32_e32 v132, v132
	v_mov_b32_e32 v152, v158
	v_mul_f32_e32 v104, v104, v132
	v_mul_f32_e32 v104, v129, v104
	v_fma_f32 v129, v133, v145, v136
	v_add_f32_e32 v129, v129, v137
	v_add_f32_e32 v129, v153, v129
	v_mul_f32_e32 v132, 0xbfb8aa3b, v129
	v_exp_f32_e32 v132, v132
	v_mov_b32_dpp v100, v113 row_ror:1 row_mask:0xf bank_mask:0xf
	v_mov_b32_dpp v144, v138 row_shr:1 row_mask:0xf bank_mask:0xf bound_ctrl:1
	v_add_f32_e32 v132, 1.0, v132
	v_rcp_f32_e32 v132, v132
	v_mov_b32_dpp v100, v105 row_shr:1 row_mask:0xf bank_mask:0xf
	v_mov_b32_dpp v136, v134 row_ror:1 row_mask:0xf bank_mask:0xf
	v_mul_f32_e32 v129, v129, v132
	v_pk_mul_f32 v[132:133], v[148:149], v[186:187]
	v_mul_f32_e32 v109, v109, v129
	v_fma_f32 v113, v113, v145, v132
	v_add_f32_e32 v113, v113, v133
	v_add_f32_e32 v113, v153, v113
	v_mul_f32_e32 v129, 0xbfb8aa3b, v113
	v_exp_f32_e32 v129, v129
	v_mov_b32_dpp v137, v106 row_ror:15 row_mask:0xf bank_mask:0xf
	v_add_f32_e32 v129, 1.0, v129
	v_rcp_f32_e32 v129, v129
	v_mov_b32_dpp v132, v138 row_ror:1 row_mask:0xf bank_mask:0xf
	v_mov_b32_dpp v133, v114 row_ror:15 row_mask:0xf bank_mask:0xf
	v_mov_b32_dpp v136, v114 row_shr:1 row_mask:0xf bank_mask:0xf
	v_mul_f32_e32 v113, v113, v129
	v_mul_f32_e32 v113, v101, v113
	v_mov_b32_dpp v132, v134 row_shr:1 row_mask:0xf bank_mask:0xf
	v_mov_b32_dpp v133, v134 row_shl:1 row_mask:0xf bank_mask:0xf
	v_mov_b32_dpp v101, v105 row_shl:1 row_mask:0xf bank_mask:0xf bound_ctrl:1
	v_pk_mul_f32 v[100:101], v[148:149], v[100:101]
	v_mov_b32_dpp v137, v114 row_shl:1 row_mask:0xf bank_mask:0xf
	v_fma_f32 v100, v105, v145, v100
	v_add_f32_e32 v100, v100, v101
	v_add_f32_e32 v100, v153, v100
	v_mul_f32_e32 v101, 0xbfb8aa3b, v100
	v_exp_f32_e32 v101, v101
	v_mov_b32_e32 v153, v150
	v_pk_mul_f32 v[132:133], v[152:153], v[132:133]
	v_add_f32_e32 v101, 1.0, v101
	v_rcp_f32_e32 v101, v101
	v_mov_b32_dpp v145, v134 row_ror:15 row_mask:0xf bank_mask:0xf
	s_nop 1
	v_mov_b32_dpp v145, v138 row_shl:1 row_mask:0xf bank_mask:0xf
	v_mul_f32_e32 v100, v100, v101
	v_pk_mul_f32 v[144:145], v[152:153], v[144:145]
	v_mul_f32_e32 v100, v97, v100
	v_fma_f32 v97, v138, v146, v144
	v_add_f32_e32 v97, v97, v145
	v_add_f32_e32 v97, v154, v97
	v_mul_f32_e32 v101, 0xbfb8aa3b, v97
	v_exp_f32_e32 v101, v101
	v_mov_b32_dpp v148, v114 row_ror:1 row_mask:0xf bank_mask:0xf
	v_mov_b32_dpp v149, v106 row_shl:1 row_mask:0xf bank_mask:0xf bound_ctrl:1
	v_add_f32_e32 v101, 1.0, v101
	v_rcp_f32_e32 v101, v101
	v_mov_b32_dpp v148, v106 row_shr:1 row_mask:0xf bank_mask:0xf
	v_mov_b32_dpp v145, v135 row_ror:15 row_mask:0xf bank_mask:0xf
	v_mul_f32_e32 v97, v97, v101
	v_fma_f32 v101, v134, v146, v132
	v_add_f32_e32 v101, v101, v133
	v_add_f32_e32 v101, v154, v101
	v_mul_f32_e32 v105, 0xbfb8aa3b, v101
	v_exp_f32_e32 v105, v105
	v_pk_mul_f32 v[132:133], v[152:153], v[136:137]
	v_mov_b32_dpp v144, v139 row_shr:1 row_mask:0xf bank_mask:0xf bound_ctrl:1
	v_mov_b32_dpp v145, v139 row_shl:1 row_mask:0xf bank_mask:0xf
	v_add_f32_e32 v105, 1.0, v105
	v_rcp_f32_e32 v105, v105
	v_mov_b32_e32 v150, v159
	v_pk_mul_f32 v[144:145], v[150:151], v[144:145]
	v_mul_f32_e32 v97, v130, v97
	v_mul_f32_e32 v101, v101, v105
	v_fma_f32 v105, v114, v146, v132
	v_add_f32_e32 v105, v105, v133
	v_add_f32_e32 v105, v154, v105
	v_mul_f32_e32 v101, v110, v101
	v_mul_f32_e32 v110, 0xbfb8aa3b, v105
	v_exp_f32_e32 v110, v110
	v_pk_mul_f32 v[132:133], v[152:153], v[148:149]
	v_add_f32_e32 v110, 1.0, v110
	v_rcp_f32_e32 v110, v110
	v_mov_b32_dpp v136, v135 row_ror:1 row_mask:0xf bank_mask:0xf
	v_mov_b32_dpp v137, v107 row_ror:15 row_mask:0xf bank_mask:0xf
	v_mov_b32_e32 v134, v140
	v_mul_f32_e32 v105, v105, v110
	v_mul_f32_e32 v102, v102, v105
	v_fma_f32 v105, v106, v146, v132
	v_add_f32_e32 v105, v105, v133
	v_add_f32_e32 v105, v154, v105
	v_mul_f32_e32 v106, 0xbfb8aa3b, v105
	v_exp_f32_e32 v106, v106
	v_mov_b32_dpp v136, v115 row_shr:1 row_mask:0xf bank_mask:0xf
	v_add_f32_e32 v106, 1.0, v106
	v_rcp_f32_e32 v106, v106
	v_mov_b32_dpp v132, v139 row_ror:1 row_mask:0xf bank_mask:0xf
	v_mov_b32_dpp v133, v115 row_ror:15 row_mask:0xf bank_mask:0xf
	v_mov_b32_dpp v137, v115 row_shl:1 row_mask:0xf bank_mask:0xf
	v_mul_f32_e32 v105, v105, v106
	v_mul_f32_e32 v98, v98, v105
	v_fma_f32 v105, v139, v147, v144
	v_add_f32_e32 v105, v105, v145
	v_add_f32_e32 v105, v155, v105
	v_mul_f32_e32 v106, 0xbfb8aa3b, v105
	v_exp_f32_e32 v106, v106
	v_mov_b32_dpp v132, v135 row_shr:1 row_mask:0xf bank_mask:0xf
	v_mov_b32_dpp v133, v135 row_shl:1 row_mask:0xf bank_mask:0xf
	v_add_f32_e32 v106, 1.0, v106
	v_rcp_f32_e32 v106, v106
	v_mov_b32_dpp v110, v115 row_ror:1 row_mask:0xf bank_mask:0xf
	v_mul_f32_e32 v105, v105, v106
	v_mul_f32_e32 v105, v131, v105
	v_pk_mul_f32 v[130:131], v[150:151], v[132:133]
	v_mov_b32_dpp v110, v107 row_shr:1 row_mask:0xf bank_mask:0xf
	v_fma_f32 v106, v135, v147, v130
	v_add_f32_e32 v106, v106, v131
	v_add_f32_e32 v106, v155, v106
	v_mul_f32_e32 v114, 0xbfb8aa3b, v106
	v_exp_f32_e32 v114, v114
	v_pk_mul_f32 v[130:131], v[150:151], v[136:137]
	v_mov_b32_e32 v135, v120
	v_add_f32_e32 v114, 1.0, v114
	v_rcp_f32_e32 v114, v114
	v_mov_b32_dpp v132, v80 row_ror:1 row_mask:0xf bank_mask:0xf
	v_mov_b32_e32 v120, v141
	v_mul_f32_e32 v106, v106, v114
	v_mul_f32_e32 v106, v111, v106
	v_fma_f32 v111, v115, v147, v130
	v_add_f32_e32 v111, v111, v131
	v_add_f32_e32 v111, v155, v111
	v_mul_f32_e32 v114, 0xbfb8aa3b, v111
	v_exp_f32_e32 v114, v114
	s_nop 0
	v_add_f32_e32 v114, 1.0, v114
	v_rcp_f32_e32 v114, v114
	v_mov_b32_dpp v131, v88 row_ror:15 row_mask:0xf bank_mask:0xf
	v_mov_b32_dpp v130, v92 row_shr:1 row_mask:0xf bank_mask:0xf bound_ctrl:1
	v_mov_b32_dpp v115, v72 row_ror:15 row_mask:0xf bank_mask:0xf
	v_mul_f32_e32 v111, v111, v114
	v_mul_f32_e32 v103, v103, v111
	v_mov_b32_dpp v131, v92 row_shl:1 row_mask:0xf bank_mask:0xf
	v_pk_mul_f32 v[130:131], v[134:135], v[130:131]
	v_mov_b32_dpp v111, v107 row_shl:1 row_mask:0xf bank_mask:0xf bound_ctrl:1
	v_pk_mul_f32 v[110:111], v[150:151], v[110:111]
	v_fma_f32 v107, v107, v147, v110
	v_add_f32_e32 v107, v107, v111
	v_add_f32_e32 v107, v155, v107
	v_mul_f32_e32 v110, 0xbfb8aa3b, v107
	v_exp_f32_e32 v110, v110
	v_mov_b32_dpp v114, v88 row_ror:1 row_mask:0xf bank_mask:0xf
	v_mov_b32_dpp v115, v80 row_shl:1 row_mask:0xf bank_mask:0xf
	v_add_f32_e32 v110, 1.0, v110
	v_rcp_f32_e32 v110, v110
	v_mov_b32_dpp v111, v80 row_ror:15 row_mask:0xf bank_mask:0xf
	v_mov_b32_dpp v114, v80 row_shr:1 row_mask:0xf bank_mask:0xf
	v_mov_b32_dpp v132, v72 row_shr:1 row_mask:0xf bank_mask:0xf
	v_mul_f32_e32 v107, v107, v110
	v_mul_f32_e32 v99, v99, v107
	v_mov_b32_dpp v111, v88 row_shl:1 row_mask:0xf bank_mask:0xf
	v_mov_b32_dpp v110, v92 row_ror:1 row_mask:0xf bank_mask:0xf
	v_fma_f32 v92, v92, v116, v130
	v_add_f32_e32 v92, v92, v131
	v_add_f32_e32 v92, v124, v92
	v_mul_f32_e32 v107, 0xbfb8aa3b, v92
	v_exp_f32_e32 v107, v107
	v_mov_b32_dpp v110, v88 row_shr:1 row_mask:0xf bank_mask:0xf
	v_pk_mul_f32 v[110:111], v[134:135], v[110:111]
	v_mov_b32_dpp v133, v72 row_shl:1 row_mask:0xf bank_mask:0xf bound_ctrl:1
	v_add_f32_e32 v107, 1.0, v107
	v_rcp_f32_e32 v107, v107
	v_fma_f32 v88, v88, v116, v110
	v_add_f32_e32 v88, v88, v111
	v_add_f32_e32 v88, v124, v88
	v_mul_f32_e32 v92, v92, v107
	v_mul_f32_e32 v84, v84, v92
	v_mul_f32_e32 v92, 0xbfb8aa3b, v88
	v_exp_f32_e32 v92, v92
	v_pk_mul_f32 v[110:111], v[134:135], v[114:115]
	v_fma_f32 v80, v80, v116, v110
	v_add_f32_e32 v92, 1.0, v92
	v_rcp_f32_e32 v92, v92
	v_add_f32_e32 v80, v80, v111
	v_add_f32_e32 v80, v124, v80
	v_pk_mul_f32 v[110:111], v[134:135], v[132:133]
	v_mul_f32_e32 v88, v88, v92
	v_mul_f32_e32 v76, v76, v88
	v_mul_f32_e32 v88, 0xbfb8aa3b, v80
	v_exp_f32_e32 v88, v88
	v_fma_f32 v72, v72, v116, v110
	v_add_f32_e32 v72, v72, v111
	v_add_f32_e32 v72, v124, v72
	v_add_f32_e32 v88, 1.0, v88
	v_rcp_f32_e32 v88, v88
	v_mov_b32_dpp v131, v89 row_ror:15 row_mask:0xf bank_mask:0xf
	v_mul_f32_e32 v80, v80, v88
	v_mul_f32_e32 v68, v68, v80
	v_mul_f32_e32 v80, 0xbfb8aa3b, v72
	v_exp_f32_e32 v80, v80
	v_mov_b32_dpp v130, v93 row_shr:1 row_mask:0xf bank_mask:0xf bound_ctrl:1
	v_mov_b32_dpp v131, v93 row_shl:1 row_mask:0xf bank_mask:0xf
	v_pk_mul_f32 v[130:131], v[120:121], v[130:131]
	v_add_f32_e32 v80, 1.0, v80
	v_rcp_f32_e32 v80, v80
	v_mov_b32_dpp v110, v93 row_ror:1 row_mask:0xf bank_mask:0xf
	v_mul_f32_e32 v72, v72, v80
	v_mul_f32_e32 v64, v64, v72
	v_fma_f32 v72, v93, v117, v130
	v_add_f32_e32 v72, v72, v131
	v_add_f32_e32 v72, v125, v72
	v_mul_f32_e32 v88, 0xbfb8aa3b, v72
	v_exp_f32_e32 v88, v88
	v_mov_b32_dpp v111, v81 row_ror:15 row_mask:0xf bank_mask:0xf
	v_mov_b32_dpp v110, v89 row_shr:1 row_mask:0xf bank_mask:0xf
	v_add_f32_e32 v88, 1.0, v88
	v_rcp_f32_e32 v88, v88
	v_mov_b32_dpp v111, v89 row_shl:1 row_mask:0xf bank_mask:0xf
	v_pk_mul_f32 v[92:93], v[120:121], v[110:111]
	v_mov_b32_dpp v114, v89 row_ror:1 row_mask:0xf bank_mask:0xf
	v_mul_f32_e32 v72, v72, v88
	v_mul_f32_e32 v85, v85, v72
	v_fma_f32 v72, v89, v117, v92
	v_add_f32_e32 v72, v72, v93
	v_add_f32_e32 v72, v125, v72
	v_mul_f32_e32 v88, 0xbfb8aa3b, v72
	v_exp_f32_e32 v88, v88
	v_mov_b32_dpp v115, v73 row_ror:15 row_mask:0xf bank_mask:0xf
	v_mov_b32_dpp v114, v81 row_shr:1 row_mask:0xf bank_mask:0xf
	v_add_f32_e32 v88, 1.0, v88
	v_rcp_f32_e32 v88, v88
	v_mov_b32_dpp v115, v81 row_shl:1 row_mask:0xf bank_mask:0xf
	v_mov_b32_dpp v80, v81 row_ror:1 row_mask:0xf bank_mask:0xf
	v_mov_b32_e32 v110, v142
	v_mul_f32_e32 v72, v72, v88
	v_pk_mul_f32 v[88:89], v[120:121], v[114:115]
	v_mul_f32_e32 v77, v77, v72
	v_fma_f32 v72, v81, v117, v88
	v_add_f32_e32 v72, v72, v89
	v_add_f32_e32 v72, v125, v72
	v_mul_f32_e32 v81, 0xbfb8aa3b, v72
	v_exp_f32_e32 v81, v81
	v_mov_b32_dpp v80, v73 row_shr:1 row_mask:0xf bank_mask:0xf
	v_mov_b32_e32 v111, v122
	v_add_f32_e32 v81, 1.0, v81
	v_rcp_f32_e32 v81, v81
	v_mov_b32_dpp v92, v82 row_ror:1 row_mask:0xf bank_mask:0xf
	v_mov_b32_e32 v122, v143
	v_mul_f32_e32 v72, v72, v81
	v_mul_f32_e32 v69, v69, v72
	v_mov_b32_dpp v92, v74 row_shr:1 row_mask:0xf bank_mask:0xf
	v_mov_b32_dpp v81, v73 row_shl:1 row_mask:0xf bank_mask:0xf bound_ctrl:1
	v_pk_mul_f32 v[80:81], v[120:121], v[80:81]
	v_mov_b32_dpp v93, v74 row_shl:1 row_mask:0xf bank_mask:0xf bound_ctrl:1
	v_fma_f32 v72, v73, v117, v80
	v_add_f32_e32 v72, v72, v81
	v_add_f32_e32 v72, v125, v72
	v_mul_f32_e32 v73, 0xbfb8aa3b, v72
	v_exp_f32_e32 v73, v73
	s_nop 0
	v_add_f32_e32 v73, 1.0, v73
	v_rcp_f32_e32 v73, v73
	v_mov_b32_dpp v80, v90 row_ror:1 row_mask:0xf bank_mask:0xf
	v_mov_b32_dpp v81, v74 row_ror:15 row_mask:0xf bank_mask:0xf
	v_mov_b32_dpp v89, v90 row_ror:15 row_mask:0xf bank_mask:0xf
	v_mul_f32_e32 v72, v72, v73
	v_mul_f32_e32 v65, v65, v72
	v_mov_b32_dpp v80, v82 row_shr:1 row_mask:0xf bank_mask:0xf
	v_mov_b32_dpp v72, v94 row_ror:1 row_mask:0xf bank_mask:0xf
	v_mov_b32_dpp v73, v82 row_ror:15 row_mask:0xf bank_mask:0xf
	v_mov_b32_dpp v81, v82 row_shl:1 row_mask:0xf bank_mask:0xf
	v_mov_b32_dpp v72, v90 row_shr:1 row_mask:0xf bank_mask:0xf
	v_mov_b32_dpp v73, v90 row_shl:1 row_mask:0xf bank_mask:0xf
	v_pk_mul_f32 v[72:73], v[110:111], v[72:73]
	v_fma_f32 v72, v90, v118, v72
	v_add_f32_e32 v72, v72, v73
	v_add_f32_e32 v72, v126, v72
	v_mul_f32_e32 v73, 0xbfb8aa3b, v72
	v_exp_f32_e32 v73, v73
	v_mov_b32_dpp v88, v94 row_shr:1 row_mask:0xf bank_mask:0xf bound_ctrl:1
	v_mov_b32_dpp v89, v94 row_shl:1 row_mask:0xf bank_mask:0xf
	v_pk_mul_f32 v[88:89], v[110:111], v[88:89]
	v_add_f32_e32 v73, 1.0, v73
	v_rcp_f32_e32 v73, v73
	v_fma_f32 v88, v94, v118, v88
	v_add_f32_e32 v88, v88, v89
	v_add_f32_e32 v88, v126, v88
	v_mul_f32_e32 v72, v72, v73
	v_mul_f32_e32 v78, v78, v72
	v_pk_mul_f32 v[72:73], v[110:111], v[80:81]
	v_fma_f32 v72, v82, v118, v72
	v_add_f32_e32 v72, v72, v73
	v_add_f32_e32 v72, v126, v72
	v_mul_f32_e32 v73, 0xbfb8aa3b, v72
	v_exp_f32_e32 v73, v73
	v_mov_b32_dpp v80, v91 row_ror:1 row_mask:0xf bank_mask:0xf
	v_mul_f32_e32 v89, 0xbfb8aa3b, v88
	v_add_f32_e32 v73, 1.0, v73
	v_rcp_f32_e32 v73, v73
	v_mov_b32_dpp v81, v75 row_ror:15 row_mask:0xf bank_mask:0xf
	v_mov_b32_dpp v80, v83 row_shr:1 row_mask:0xf bank_mask:0xf
	v_exp_f32_e32 v89, v89
	v_mul_f32_e32 v72, v72, v73
	v_mul_f32_e32 v82, v70, v72
	v_pk_mul_f32 v[72:73], v[110:111], v[92:93]
	v_mov_b32_dpp v81, v83 row_shl:1 row_mask:0xf bank_mask:0xf
	v_fma_f32 v70, v74, v118, v72
	v_add_f32_e32 v70, v70, v73
	v_add_f32_e32 v70, v126, v70
	v_mul_f32_e32 v72, 0xbfb8aa3b, v70
	v_exp_f32_e32 v72, v72
	v_add_f32_e32 v89, 1.0, v89
	v_rcp_f32_e32 v89, v89
	v_add_f32_e32 v72, 1.0, v72
	v_rcp_f32_e32 v72, v72
	v_mov_b32_dpp v73, v83 row_ror:15 row_mask:0xf bank_mask:0xf
	v_mul_f32_e32 v88, v88, v89
	v_mul_f32_e32 v70, v70, v72
	v_mov_b32_dpp v73, v91 row_shl:1 row_mask:0xf bank_mask:0xf
	v_mul_f32_e32 v86, v86, v88
	v_mov_b32_dpp v72, v95 row_ror:1 row_mask:0xf bank_mask:0xf
	v_mul_f32_e32 v74, v66, v70
	v_mov_b32_dpp v89, v91 row_ror:15 row_mask:0xf bank_mask:0xf
	v_mov_b32_dpp v72, v91 row_shr:1 row_mask:0xf bank_mask:0xf
	v_pk_mul_f32 v[72:73], v[122:123], v[72:73]
	v_fma_f32 v72, v91, v119, v72
	v_add_f32_e32 v72, v72, v73
	v_add_f32_e32 v72, v127, v72
	v_mul_f32_e32 v73, 0xbfb8aa3b, v72
	v_exp_f32_e32 v73, v73
	v_mov_b32_dpp v70, v83 row_ror:1 row_mask:0xf bank_mask:0xf
	v_mov_b32_dpp v89, v95 row_shl:1 row_mask:0xf bank_mask:0xf
	v_add_f32_e32 v73, 1.0, v73
	v_rcp_f32_e32 v73, v73
	v_mov_b32_dpp v88, v95 row_shr:1 row_mask:0xf bank_mask:0xf bound_ctrl:1
	v_pk_mul_f32 v[88:89], v[122:123], v[88:89]
	v_mov_b32_dpp v70, v75 row_shr:1 row_mask:0xf bank_mask:0xf
	v_mul_f32_e32 v72, v72, v73
	v_mul_f32_e32 v79, v79, v72
	v_pk_mul_f32 v[72:73], v[122:123], v[80:81]
	v_fma_f32 v66, v95, v119, v88
	v_fma_f32 v72, v83, v119, v72
	v_add_f32_e32 v72, v72, v73
	v_add_f32_e32 v72, v127, v72
	v_mul_f32_e32 v73, 0xbfb8aa3b, v72
	v_exp_f32_e32 v73, v73
	v_add_f32_e32 v66, v66, v89
	v_add_f32_e32 v66, v127, v66
	v_mul_f32_e32 v88, 0xbfb8aa3b, v66
	v_add_f32_e32 v73, 1.0, v73
	v_rcp_f32_e32 v73, v73
	v_exp_f32_e32 v88, v88
	v_mul_f32_e32 v72, v72, v73
	v_mul_f32_e32 v80, v71, v72
	v_add_f32_e32 v88, 1.0, v88
	v_rcp_f32_e32 v88, v88
	v_mov_b32_dpp v71, v75 row_shl:1 row_mask:0xf bank_mask:0xf bound_ctrl:1
	v_pk_mul_f32 v[70:71], v[122:123], v[70:71]
	v_mul_f32_e32 v66, v66, v88
	v_fma_f32 v70, v75, v119, v70
	v_add_f32_e32 v70, v70, v71
	v_add_f32_e32 v70, v127, v70
	v_mul_f32_e32 v71, 0xbfb8aa3b, v70
	v_exp_f32_e32 v71, v71
	v_mul_f32_e32 v66, v87, v66
	v_add_f32_e32 v71, 1.0, v71
	v_rcp_f32_e32 v71, v71
	s_nop 0
	v_mul_f32_e32 v70, v70, v71
	v_mul_f32_e32 v75, v67, v70
	v_cvt_pk_bf16_f32 v70, v128, v104
	v_cvt_pk_bf16_f32 v71, v97, v105
	v_cvt_pk_bf16_f32 v72, v84, v85
	v_cvt_pk_bf16_f32 v73, v86, v66
	v_mul_lo_u32 v66, v194, s17
	v_add_lshl_u32 v97, v66, v184, 1
	buffer_store_dwordx4 v[70:73], v97, s[24:27], 0 offen sc1
	v_add_u32_e32 v66, 0x16000, v97
	s_nop 0
	v_cvt_pk_bf16_f32 v70, v108, v109
	v_cvt_pk_bf16_f32 v71, v101, v106
	v_cvt_pk_bf16_f32 v72, v76, v77
	v_cvt_pk_bf16_f32 v73, v78, v79
	buffer_store_dwordx4 v[70:73], v66, s[24:27], 0 offen sc1
	v_cvt_pk_bf16_f32 v66, v112, v113
	v_cvt_pk_bf16_f32 v67, v102, v103
	v_cvt_pk_bf16_f32 v68, v68, v69
	v_cvt_pk_bf16_f32 v69, v82, v80
	s_nop 0
	v_add_u32_e32 v70, 0x2c000, v97
	buffer_store_dwordx4 v[66:69], v70, s[24:27], 0 offen sc1
	v_mov_b32_dpp v103, v56 row_ror:15 row_mask:0xf bank_mask:0xf
	s_nop 0
	v_cvt_pk_bf16_f32 v66, v96, v100
	v_cvt_pk_bf16_f32 v67, v98, v99
	v_cvt_pk_bf16_f32 v68, v64, v65
	v_add_u32_e32 v64, 0x42000, v97
	v_cvt_pk_bf16_f32 v69, v74, v75
	buffer_store_dwordx4 v[66:69], v64, s[24:27], 0 offen sc1
	global_load_dwordx4 v[76:79], v[182:183], off offset:16
	global_load_dwordx4 v[92:95], v[182:183], off
	s_nop 0
	global_load_dwordx4 v[64:67], v[180:181], off offset:16
	global_load_dwordx4 v[80:83], v[180:181], off
	global_load_dwordx4 v[68:71], v[178:179], off offset:16
	global_load_dwordx4 v[84:87], v[178:179], off
	global_load_dwordx4 v[72:75], v[176:177], off offset:16
	global_load_dwordx4 v[88:91], v[176:177], off
	v_mov_b32_dpp v102, v60 row_shr:1 row_mask:0xf bank_mask:0xf bound_ctrl:1
	v_mov_b32_dpp v103, v60 row_shl:1 row_mask:0xf bank_mask:0xf
	v_mov_b32_dpp v98, v60 row_ror:1 row_mask:0xf bank_mask:0xf
	v_mov_b32_dpp v99, v48 row_ror:15 row_mask:0xf bank_mask:0xf
	v_mov_b32_dpp v100, v56 row_ror:1 row_mask:0xf bank_mask:0xf
	v_mov_b32_dpp v98, v56 row_shr:1 row_mask:0xf bank_mask:0xf
	v_mov_b32_dpp v99, v56 row_shl:1 row_mask:0xf bank_mask:0xf
	v_mov_b32_dpp v100, v48 row_shr:1 row_mask:0xf bank_mask:0xf
	v_mov_b32_dpp v104, v48 row_ror:1 row_mask:0xf bank_mask:0xf
	v_mov_b32_dpp v101, v40 row_ror:15 row_mask:0xf bank_mask:0xf
	s_nop 0
	v_mov_b32_dpp v104, v40 row_shr:1 row_mask:0xf bank_mask:0xf
	s_nop 0
	v_mov_b32_dpp v101, v48 row_shl:1 row_mask:0xf bank_mask:0xf
	v_mov_b32_dpp v105, v40 row_shl:1 row_mask:0xf bank_mask:0xf bound_ctrl:1
	s_waitcnt vmcnt(6)
	v_mov_b32_e32 v106, v92
	s_waitcnt vmcnt(2)
	v_mov_b32_e32 v107, v84
	v_pk_mul_f32 v[102:103], v[106:107], v[102:103]
	v_pk_mul_f32 v[98:99], v[106:107], v[98:99]
	v_fma_f32 v60, v60, v80, v102
	v_add_f32_e32 v60, v60, v103
	s_waitcnt vmcnt(0)
	v_add_f32_e32 v60, v88, v60
	v_mul_f32_e32 v84, 0xbfb8aa3b, v60
	v_exp_f32_e32 v84, v84
	v_fma_f32 v56, v56, v80, v98
	v_add_f32_e32 v56, v56, v99
	v_add_f32_e32 v56, v88, v56
	v_add_f32_e32 v84, 1.0, v84
	v_rcp_f32_e32 v84, v84
	v_pk_mul_f32 v[98:99], v[106:107], v[100:101]
	v_fma_f32 v48, v48, v80, v98
	v_mul_f32_e32 v60, v60, v84
	v_mul_f32_e32 v52, v52, v60
	v_mul_f32_e32 v60, 0xbfb8aa3b, v56
	v_exp_f32_e32 v60, v60
	v_add_f32_e32 v48, v48, v99
	v_add_f32_e32 v48, v88, v48
	v_pk_mul_f32 v[98:99], v[106:107], v[104:105]
	v_add_f32_e32 v60, 1.0, v60
	v_rcp_f32_e32 v60, v60
	v_fma_f32 v40, v40, v80, v98
	v_add_f32_e32 v40, v40, v99
	v_add_f32_e32 v40, v88, v40
	v_mul_f32_e32 v56, v56, v60
	v_mul_f32_e32 v44, v44, v56
	v_mul_f32_e32 v56, 0xbfb8aa3b, v48
	v_exp_f32_e32 v56, v56
	v_mov_b32_dpp v103, v57 row_ror:15 row_mask:0xf bank_mask:0xf
	v_mov_b32_e32 v84, v93
	v_add_f32_e32 v56, 1.0, v56
	v_rcp_f32_e32 v56, v56
	v_mov_b32_dpp v102, v61 row_shr:1 row_mask:0xf bank_mask:0xf bound_ctrl:1
	v_mov_b32_dpp v103, v61 row_shl:1 row_mask:0xf bank_mask:0xf
	v_pk_mul_f32 v[92:93], v[84:85], v[102:103]
	v_mul_f32_e32 v48, v48, v56
	v_mul_f32_e32 v36, v36, v48
	v_mul_f32_e32 v48, 0xbfb8aa3b, v40
	v_exp_f32_e32 v48, v48
	s_nop 0
	v_add_f32_e32 v48, 1.0, v48
	v_rcp_f32_e32 v48, v48
	v_mov_b32_dpp v98, v61 row_ror:1 row_mask:0xf bank_mask:0xf
	v_mov_b32_dpp v99, v49 row_ror:15 row_mask:0xf bank_mask:0xf
	v_mul_f32_e32 v40, v40, v48
	v_mul_f32_e32 v32, v32, v40
	v_fma_f32 v40, v61, v81, v92
	v_add_f32_e32 v40, v40, v93
	v_add_f32_e32 v40, v89, v40
	v_mul_f32_e32 v56, 0xbfb8aa3b, v40
	v_exp_f32_e32 v56, v56
	v_mov_b32_dpp v98, v57 row_shr:1 row_mask:0xf bank_mask:0xf
	v_mov_b32_dpp v99, v57 row_shl:1 row_mask:0xf bank_mask:0xf
	v_pk_mul_f32 v[60:61], v[84:85], v[98:99]
	v_add_f32_e32 v56, 1.0, v56
	v_rcp_f32_e32 v56, v56
	v_mov_b32_dpp v100, v57 row_ror:1 row_mask:0xf bank_mask:0xf
	v_mov_b32_dpp v101, v41 row_ror:15 row_mask:0xf bank_mask:0xf
	v_mul_f32_e32 v40, v40, v56
	v_mul_f32_e32 v40, v53, v40
	v_fma_f32 v53, v57, v81, v60
	v_add_f32_e32 v53, v53, v61
	v_add_f32_e32 v53, v89, v53
	v_mul_f32_e32 v56, 0xbfb8aa3b, v53
	v_exp_f32_e32 v56, v56
	v_mov_b32_dpp v100, v49 row_shr:1 row_mask:0xf bank_mask:0xf
	v_mov_b32_dpp v101, v49 row_shl:1 row_mask:0xf bank_mask:0xf
	v_mov_b32_dpp v48, v49 row_ror:1 row_mask:0xf bank_mask:0xf
	v_add_f32_e32 v56, 1.0, v56
	v_rcp_f32_e32 v56, v56
	v_mov_b32_dpp v48, v41 row_shr:1 row_mask:0xf bank_mask:0xf
	v_mul_f32_e32 v53, v53, v56
	v_pk_mul_f32 v[56:57], v[84:85], v[100:101]
	v_mul_f32_e32 v45, v45, v53
	v_fma_f32 v49, v49, v81, v56
	v_add_f32_e32 v49, v49, v57
	v_add_f32_e32 v49, v89, v49
	v_mul_f32_e32 v53, 0xbfb8aa3b, v49
	v_exp_f32_e32 v53, v53
	v_mov_b32_dpp v80, v50 row_ror:1 row_mask:0xf bank_mask:0xf
	v_add_f32_e32 v53, 1.0, v53
	v_rcp_f32_e32 v53, v53
	v_mov_b32_dpp v56, v58 row_ror:1 row_mask:0xf bank_mask:0xf
	v_mov_b32_dpp v57, v42 row_ror:15 row_mask:0xf bank_mask:0xf
	v_mov_b32_dpp v80, v42 row_shr:1 row_mask:0xf bank_mask:0xf
	v_mul_f32_e32 v49, v49, v53
	v_mul_f32_e32 v37, v37, v49
	v_mov_b32_dpp v56, v50 row_shr:1 row_mask:0xf bank_mask:0xf
	v_mov_b32_dpp v57, v50 row_shl:1 row_mask:0xf bank_mask:0xf
	v_mov_b32_dpp v49, v41 row_shl:1 row_mask:0xf bank_mask:0xf bound_ctrl:1
	v_pk_mul_f32 v[48:49], v[84:85], v[48:49]
	v_mov_b32_e32 v84, v94
	v_fma_f32 v41, v41, v81, v48
	v_add_f32_e32 v41, v41, v49
	v_add_f32_e32 v41, v89, v41
	v_mul_f32_e32 v48, 0xbfb8aa3b, v41
	v_exp_f32_e32 v48, v48
	v_mov_b32_e32 v85, v86
	v_add_f32_e32 v48, 1.0, v48
	v_rcp_f32_e32 v48, v48
	v_mov_b32_dpp v49, v50 row_ror:15 row_mask:0xf bank_mask:0xf
	v_mov_b32_dpp v81, v42 row_shl:1 row_mask:0xf bank_mask:0xf bound_ctrl:1
	v_mov_b32_e32 v86, v95
	v_mul_f32_e32 v41, v41, v48
	v_mov_b32_dpp v49, v58 row_shl:1 row_mask:0xf bank_mask:0xf
	v_mov_b32_dpp v61, v58 row_ror:15 row_mask:0xf bank_mask:0xf
	v_mov_b32_dpp v48, v62 row_ror:1 row_mask:0xf bank_mask:0xf
	s_nop 0
	v_mov_b32_dpp v61, v62 row_shl:1 row_mask:0xf bank_mask:0xf
	s_nop 0
	v_mov_b32_dpp v48, v58 row_shr:1 row_mask:0xf bank_mask:0xf
	v_pk_mul_f32 v[48:49], v[84:85], v[48:49]
	v_mov_b32_dpp v60, v62 row_shr:1 row_mask:0xf bank_mask:0xf bound_ctrl:1
	v_fma_f32 v48, v58, v82, v48
	v_add_f32_e32 v48, v48, v49
	v_add_f32_e32 v48, v90, v48
	v_mul_f32_e32 v49, 0xbfb8aa3b, v48
	v_exp_f32_e32 v49, v49
	v_pk_mul_f32 v[60:61], v[84:85], v[60:61]
	v_mul_f32_e32 v33, v33, v41
	v_fma_f32 v41, v62, v82, v60
	v_add_f32_e32 v49, 1.0, v49
	v_rcp_f32_e32 v49, v49
	v_add_f32_e32 v41, v41, v61
	v_add_f32_e32 v41, v90, v41
	v_mul_f32_e32 v53, 0xbfb8aa3b, v41
	v_mul_f32_e32 v48, v48, v49
	v_mul_f32_e32 v46, v46, v48
	v_pk_mul_f32 v[48:49], v[84:85], v[56:57]
	v_fma_f32 v48, v50, v82, v48
	v_add_f32_e32 v48, v48, v49
	v_add_f32_e32 v48, v90, v48
	v_mul_f32_e32 v49, 0xbfb8aa3b, v48
	v_exp_f32_e32 v49, v49
	v_mov_b32_dpp v56, v59 row_ror:1 row_mask:0xf bank_mask:0xf
	v_exp_f32_e32 v53, v53
	v_add_f32_e32 v49, 1.0, v49
	v_rcp_f32_e32 v49, v49
	v_mov_b32_dpp v57, v43 row_ror:15 row_mask:0xf bank_mask:0xf
	v_mov_b32_dpp v56, v51 row_shr:1 row_mask:0xf bank_mask:0xf
	v_mul_f32_e32 v48, v48, v49
	v_mul_f32_e32 v38, v38, v48
	v_pk_mul_f32 v[48:49], v[84:85], v[80:81]
	v_mov_b32_dpp v57, v51 row_shl:1 row_mask:0xf bank_mask:0xf
	v_fma_f32 v42, v42, v82, v48
	v_add_f32_e32 v42, v42, v49
	v_add_f32_e32 v42, v90, v42
	v_mul_f32_e32 v48, 0xbfb8aa3b, v42
	v_exp_f32_e32 v48, v48
	v_mov_b32_dpp v61, v59 row_ror:15 row_mask:0xf bank_mask:0xf
	v_add_f32_e32 v48, 1.0, v48
	v_rcp_f32_e32 v48, v48
	v_mov_b32_dpp v49, v51 row_ror:15 row_mask:0xf bank_mask:0xf
	v_add_f32_e32 v53, 1.0, v53
	v_mov_b32_dpp v60, v63 row_shr:1 row_mask:0xf bank_mask:0xf bound_ctrl:1
	v_mul_f32_e32 v42, v42, v48
	v_mov_b32_dpp v49, v59 row_shl:1 row_mask:0xf bank_mask:0xf
	v_mov_b32_dpp v61, v63 row_shl:1 row_mask:0xf bank_mask:0xf
	v_mov_b32_dpp v48, v63 row_ror:1 row_mask:0xf bank_mask:0xf
	v_rcp_f32_e32 v53, v53
	v_pk_mul_f32 v[60:61], v[86:87], v[60:61]
	v_mov_b32_dpp v48, v59 row_shr:1 row_mask:0xf bank_mask:0xf
	v_pk_mul_f32 v[48:49], v[86:87], v[48:49]
	v_mul_f32_e32 v34, v34, v42
	v_fma_f32 v48, v59, v83, v48
	v_add_f32_e32 v48, v48, v49
	v_add_f32_e32 v48, v91, v48
	v_mul_f32_e32 v49, 0xbfb8aa3b, v48
	v_exp_f32_e32 v49, v49
	v_fma_f32 v42, v63, v83, v60
	v_add_f32_e32 v42, v42, v61
	v_add_f32_e32 v49, 1.0, v49
	v_rcp_f32_e32 v49, v49
	v_mov_b32_dpp v50, v51 row_ror:1 row_mask:0xf bank_mask:0xf
	v_add_f32_e32 v42, v91, v42
	v_mul_f32_e32 v41, v41, v53
	v_mul_f32_e32 v48, v48, v49
	v_mul_f32_e32 v47, v47, v48
	v_pk_mul_f32 v[48:49], v[86:87], v[56:57]
	v_mov_b32_dpp v50, v43 row_shr:1 row_mask:0xf bank_mask:0xf
	v_fma_f32 v48, v51, v83, v48
	v_add_f32_e32 v48, v48, v49
	v_add_f32_e32 v48, v91, v48
	v_mul_f32_e32 v49, 0xbfb8aa3b, v48
	v_exp_f32_e32 v49, v49
	v_mul_f32_e32 v53, 0xbfb8aa3b, v42
	v_exp_f32_e32 v53, v53
	v_add_f32_e32 v49, 1.0, v49
	v_rcp_f32_e32 v49, v49
	v_mov_b32_dpp v51, v43 row_shl:1 row_mask:0xf bank_mask:0xf bound_ctrl:1
	v_add_f32_e32 v53, 1.0, v53
	v_rcp_f32_e32 v53, v53
	v_mul_f32_e32 v48, v48, v49
	v_mul_f32_e32 v39, v39, v48
	v_pk_mul_f32 v[48:49], v[86:87], v[50:51]
	v_mul_f32_e32 v42, v42, v53
	v_fma_f32 v43, v43, v83, v48
	v_add_f32_e32 v43, v43, v49
	v_add_f32_e32 v43, v91, v43
	v_mul_f32_e32 v48, 0xbfb8aa3b, v43
	v_exp_f32_e32 v48, v48
	v_mul_f32_e32 v42, v55, v42
	v_mul_f32_e32 v41, v54, v41
	v_add_f32_e32 v48, 1.0, v48
	v_rcp_f32_e32 v48, v48
	v_mov_b32_dpp v55, v24 row_ror:15 row_mask:0xf bank_mask:0xf
	v_mov_b32_e32 v58, v76
	s_nop 0
	v_mov_b32_dpp v55, v28 row_shl:1 row_mask:0xf bank_mask:0xf
	v_mov_b32_dpp v54, v28 row_shr:1 row_mask:0xf bank_mask:0xf bound_ctrl:1
	v_mov_b32_e32 v59, v68
	v_mul_f32_e32 v43, v43, v48
	v_pk_mul_f32 v[54:55], v[58:59], v[54:55]
	v_mul_f32_e32 v35, v35, v43
	v_mov_b32_dpp v48, v28 row_ror:1 row_mask:0xf bank_mask:0xf
	v_fma_f32 v28, v28, v64, v54
	v_add_f32_e32 v28, v28, v55
	v_add_f32_e32 v28, v72, v28
	v_mul_f32_e32 v43, 0xbfb8aa3b, v28
	v_exp_f32_e32 v43, v43
	v_mov_b32_dpp v48, v24 row_shr:1 row_mask:0xf bank_mask:0xf
	v_mov_b32_dpp v49, v16 row_ror:15 row_mask:0xf bank_mask:0xf
	v_add_f32_e32 v43, 1.0, v43
	v_rcp_f32_e32 v43, v43
	v_mov_b32_dpp v49, v24 row_shl:1 row_mask:0xf bank_mask:0xf
	v_pk_mul_f32 v[48:49], v[58:59], v[48:49]
	v_mov_b32_dpp v50, v24 row_ror:1 row_mask:0xf bank_mask:0xf
	v_fma_f32 v24, v24, v64, v48
	v_add_f32_e32 v24, v24, v49
	v_mul_f32_e32 v28, v28, v43
	v_add_f32_e32 v24, v72, v24
	v_mul_f32_e32 v20, v20, v28
	v_mul_f32_e32 v28, 0xbfb8aa3b, v24
	v_exp_f32_e32 v28, v28
	v_mov_b32_dpp v50, v16 row_shr:1 row_mask:0xf bank_mask:0xf
	v_mov_b32_dpp v51, v8 row_ror:15 row_mask:0xf bank_mask:0xf
	v_add_f32_e32 v28, 1.0, v28
	v_rcp_f32_e32 v28, v28
	v_mov_b32_dpp v51, v16 row_shl:1 row_mask:0xf bank_mask:0xf
	v_pk_mul_f32 v[48:49], v[58:59], v[50:51]
	v_mov_b32_dpp v56, v16 row_ror:1 row_mask:0xf bank_mask:0xf
	v_fma_f32 v16, v16, v64, v48
	v_add_f32_e32 v16, v16, v49
	v_mul_f32_e32 v24, v24, v28
	v_add_f32_e32 v16, v72, v16
	v_mul_f32_e32 v12, v12, v24
	v_mul_f32_e32 v24, 0xbfb8aa3b, v16
	v_exp_f32_e32 v24, v24
	v_mov_b32_dpp v56, v8 row_shr:1 row_mask:0xf bank_mask:0xf
	v_add_f32_e32 v24, 1.0, v24
	v_rcp_f32_e32 v24, v24
	v_mov_b32_dpp v57, v8 row_shl:1 row_mask:0xf bank_mask:0xf bound_ctrl:1
	v_pk_mul_f32 v[48:49], v[58:59], v[56:57]
	v_mov_b32_dpp v55, v25 row_ror:15 row_mask:0xf bank_mask:0xf
	v_fma_f32 v8, v8, v64, v48
	v_add_f32_e32 v8, v8, v49
	v_mul_f32_e32 v16, v16, v24
	v_add_f32_e32 v8, v72, v8
	v_mul_f32_e32 v4, v4, v16
	v_mul_f32_e32 v16, 0xbfb8aa3b, v8
	v_exp_f32_e32 v16, v16
	v_mov_b32_dpp v55, v29 row_shl:1 row_mask:0xf bank_mask:0xf
	v_mov_b32_e32 v68, v77
	v_add_f32_e32 v16, 1.0, v16
	v_rcp_f32_e32 v16, v16
	v_mov_b32_dpp v54, v29 row_shr:1 row_mask:0xf bank_mask:0xf bound_ctrl:1
	v_pk_mul_f32 v[54:55], v[68:69], v[54:55]
	v_mul_f32_e32 v8, v8, v16
	v_mul_f32_e32 v0, v0, v8
	v_fma_f32 v8, v29, v65, v54
	v_add_f32_e32 v8, v8, v55
	v_add_f32_e32 v8, v73, v8
	v_mul_f32_e32 v24, 0xbfb8aa3b, v8
	v_exp_f32_e32 v24, v24
	v_mov_b32_dpp v48, v29 row_ror:1 row_mask:0xf bank_mask:0xf
	v_add_f32_e32 v24, 1.0, v24
	v_rcp_f32_e32 v24, v24
	v_mov_b32_dpp v49, v17 row_ror:15 row_mask:0xf bank_mask:0xf
	v_mov_b32_dpp v48, v25 row_shr:1 row_mask:0xf bank_mask:0xf
	s_nop 0
	v_mov_b32_dpp v49, v25 row_shl:1 row_mask:0xf bank_mask:0xf
	v_mul_f32_e32 v8, v8, v24
	v_pk_mul_f32 v[28:29], v[68:69], v[48:49]
	v_mul_f32_e32 v21, v21, v8
	v_fma_f32 v8, v25, v65, v28
	v_add_f32_e32 v8, v8, v29
	v_add_f32_e32 v8, v73, v8
	v_mul_f32_e32 v24, 0xbfb8aa3b, v8
	v_exp_f32_e32 v24, v24
	v_mov_b32_dpp v50, v25 row_ror:1 row_mask:0xf bank_mask:0xf
	v_mov_b32_dpp v51, v9 row_ror:15 row_mask:0xf bank_mask:0xf
	v_add_f32_e32 v24, 1.0, v24
	v_rcp_f32_e32 v24, v24
	v_mov_b32_dpp v50, v17 row_shr:1 row_mask:0xf bank_mask:0xf
	v_mov_b32_dpp v51, v17 row_shl:1 row_mask:0xf bank_mask:0xf
	v_mov_b32_dpp v16, v17 row_ror:1 row_mask:0xf bank_mask:0xf
	v_mul_f32_e32 v8, v8, v24
	v_pk_mul_f32 v[24:25], v[68:69], v[50:51]
	v_mul_f32_e32 v13, v13, v8
	v_fma_f32 v8, v17, v65, v24
	v_add_f32_e32 v8, v8, v25
	v_add_f32_e32 v8, v73, v8
	v_mul_f32_e32 v17, 0xbfb8aa3b, v8
	v_exp_f32_e32 v17, v17
	v_mov_b32_dpp v16, v9 row_shr:1 row_mask:0xf bank_mask:0xf
	v_mov_b32_e32 v48, v78
	v_mov_b32_e32 v49, v70
	v_add_f32_e32 v17, 1.0, v17
	v_rcp_f32_e32 v17, v17
	v_mov_b32_e32 v70, v79
	v_mul_f32_e32 v8, v8, v17
	v_mul_f32_e32 v5, v5, v8
	v_mov_b32_dpp v28, v18 row_ror:1 row_mask:0xf bank_mask:0xf
	v_mov_b32_dpp v17, v9 row_shl:1 row_mask:0xf bank_mask:0xf bound_ctrl:1
	v_pk_mul_f32 v[16:17], v[68:69], v[16:17]
	v_mov_b32_dpp v28, v10 row_shr:1 row_mask:0xf bank_mask:0xf
	v_fma_f32 v8, v9, v65, v16
	v_add_f32_e32 v8, v8, v17
	v_add_f32_e32 v8, v73, v8
	v_mul_f32_e32 v9, 0xbfb8aa3b, v8
	v_exp_f32_e32 v9, v9
	v_mov_b32_dpp v29, v10 row_shl:1 row_mask:0xf bank_mask:0xf bound_ctrl:1
	v_add_f32_e32 v9, 1.0, v9
	v_rcp_f32_e32 v9, v9
	v_mov_b32_dpp v16, v26 row_ror:1 row_mask:0xf bank_mask:0xf
	v_mov_b32_dpp v17, v10 row_ror:15 row_mask:0xf bank_mask:0xf
	v_mul_f32_e32 v8, v8, v9
	v_mul_f32_e32 v1, v1, v8
	v_mov_b32_dpp v16, v18 row_shr:1 row_mask:0xf bank_mask:0xf
	v_mov_b32_dpp v8, v30 row_ror:1 row_mask:0xf bank_mask:0xf
	v_mov_b32_dpp v9, v18 row_ror:15 row_mask:0xf bank_mask:0xf
	v_mov_b32_dpp v17, v18 row_shl:1 row_mask:0xf bank_mask:0xf
	v_mov_b32_dpp v8, v26 row_shr:1 row_mask:0xf bank_mask:0xf
	v_mov_b32_dpp v9, v26 row_shl:1 row_mask:0xf bank_mask:0xf
	v_pk_mul_f32 v[8:9], v[48:49], v[8:9]
	v_mov_b32_dpp v25, v26 row_ror:15 row_mask:0xf bank_mask:0xf
	v_fma_f32 v8, v26, v66, v8
	v_add_f32_e32 v8, v8, v9
	v_add_f32_e32 v8, v74, v8
	v_mul_f32_e32 v9, 0xbfb8aa3b, v8
	v_exp_f32_e32 v9, v9
	v_mov_b32_dpp v25, v30 row_shl:1 row_mask:0xf bank_mask:0xf
	v_add_f32_e32 v9, 1.0, v9
	v_rcp_f32_e32 v9, v9
	v_mov_b32_dpp v24, v30 row_shr:1 row_mask:0xf bank_mask:0xf bound_ctrl:1
	v_pk_mul_f32 v[24:25], v[48:49], v[24:25]
	v_mul_f32_e32 v8, v8, v9
	v_mul_f32_e32 v14, v14, v8
	v_pk_mul_f32 v[8:9], v[48:49], v[16:17]
	v_fma_f32 v8, v18, v66, v8
	v_add_f32_e32 v8, v8, v9
	v_add_f32_e32 v8, v74, v8
	v_mul_f32_e32 v9, 0xbfb8aa3b, v8
	v_exp_f32_e32 v9, v9
	v_mov_b32_dpp v16, v27 row_ror:1 row_mask:0xf bank_mask:0xf
	v_fma_f32 v24, v30, v66, v24
	v_add_f32_e32 v9, 1.0, v9
	v_rcp_f32_e32 v9, v9
	v_mov_b32_dpp v17, v11 row_ror:15 row_mask:0xf bank_mask:0xf
	v_mov_b32_dpp v16, v19 row_shr:1 row_mask:0xf bank_mask:0xf
	v_add_f32_e32 v24, v24, v25
	v_mul_f32_e32 v8, v8, v9
	v_mul_f32_e32 v18, v6, v8
	v_pk_mul_f32 v[8:9], v[48:49], v[28:29]
	v_mov_b32_dpp v17, v19 row_shl:1 row_mask:0xf bank_mask:0xf
	v_fma_f32 v6, v10, v66, v8
	v_add_f32_e32 v6, v6, v9
	v_add_f32_e32 v6, v74, v6
	v_mul_f32_e32 v8, 0xbfb8aa3b, v6
	v_exp_f32_e32 v8, v8
	v_add_f32_e32 v24, v74, v24
	v_mul_f32_e32 v25, 0xbfb8aa3b, v24
	v_add_f32_e32 v8, 1.0, v8
	v_rcp_f32_e32 v8, v8
	v_mov_b32_dpp v9, v19 row_ror:15 row_mask:0xf bank_mask:0xf
	v_exp_f32_e32 v25, v25
	v_mul_f32_e32 v6, v6, v8
	v_mov_b32_dpp v9, v27 row_shl:1 row_mask:0xf bank_mask:0xf
	v_add_f32_e32 v25, 1.0, v25
	v_mov_b32_dpp v8, v31 row_ror:1 row_mask:0xf bank_mask:0xf
	v_rcp_f32_e32 v25, v25
	v_mul_f32_e32 v10, v2, v6
	v_mov_b32_dpp v8, v27 row_shr:1 row_mask:0xf bank_mask:0xf
	v_pk_mul_f32 v[8:9], v[70:71], v[8:9]
	v_mul_f32_e32 v24, v24, v25
	v_fma_f32 v8, v27, v67, v8
	v_add_f32_e32 v8, v8, v9
	v_add_f32_e32 v8, v75, v8
	v_mul_f32_e32 v9, 0xbfb8aa3b, v8
	v_exp_f32_e32 v9, v9
	v_mul_f32_e32 v22, v22, v24
	v_add_f32_e32 v9, 1.0, v9
	v_rcp_f32_e32 v9, v9
	v_mov_b32_dpp v25, v27 row_ror:15 row_mask:0xf bank_mask:0xf
	v_mov_b32_dpp v6, v19 row_ror:1 row_mask:0xf bank_mask:0xf
	v_mul_f32_e32 v8, v8, v9
	v_mul_f32_e32 v15, v15, v8
	v_pk_mul_f32 v[8:9], v[70:71], v[16:17]
	v_mov_b32_dpp v24, v31 row_shr:1 row_mask:0xf bank_mask:0xf bound_ctrl:1
	v_fma_f32 v8, v19, v67, v8
	v_add_f32_e32 v8, v8, v9
	v_add_f32_e32 v8, v75, v8
	v_mul_f32_e32 v9, 0xbfb8aa3b, v8
	v_exp_f32_e32 v9, v9
	v_mov_b32_dpp v25, v31 row_shl:1 row_mask:0xf bank_mask:0xf
	v_pk_mul_f32 v[24:25], v[70:71], v[24:25]
	v_mov_b32_dpp v6, v11 row_shr:1 row_mask:0xf bank_mask:0xf
	v_add_f32_e32 v9, 1.0, v9
	v_rcp_f32_e32 v9, v9
	v_fma_f32 v2, v31, v67, v24
	v_add_f32_e32 v2, v2, v25
	v_add_f32_e32 v2, v75, v2
	v_mul_f32_e32 v8, v8, v9
	v_mul_f32_e32 v16, v7, v8
	v_mul_f32_e32 v24, 0xbfb8aa3b, v2
	v_exp_f32_e32 v24, v24
	v_mov_b32_dpp v7, v11 row_shl:1 row_mask:0xf bank_mask:0xf bound_ctrl:1
	v_pk_mul_f32 v[6:7], v[70:71], v[6:7]
	v_add_f32_e32 v24, 1.0, v24
	v_fma_f32 v6, v11, v67, v6
	v_add_f32_e32 v6, v6, v7
	v_add_f32_e32 v6, v75, v6
	v_mul_f32_e32 v7, 0xbfb8aa3b, v6
	v_exp_f32_e32 v7, v7
	v_rcp_f32_e32 v24, v24
	v_add_f32_e32 v7, 1.0, v7
	v_rcp_f32_e32 v7, v7
	v_mul_f32_e32 v2, v2, v24
	v_mul_f32_e32 v2, v23, v2
	v_mul_f32_e32 v6, v6, v7
	v_mul_f32_e32 v11, v3, v6
	v_cvt_pk_bf16_f32 v6, v52, v40
	v_cvt_pk_bf16_f32 v7, v41, v42
	v_cvt_pk_bf16_f32 v8, v20, v21
	v_cvt_pk_bf16_f32 v9, v22, v2
	v_add_u32_e32 v2, 0xb0000, v97
	buffer_store_dwordx4 v[6:9], v2, s[24:27], 0 offen sc1
	v_add_u32_e32 v2, 0xc6000, v97
	s_nop 0
	v_cvt_pk_bf16_f32 v6, v44, v45
	v_cvt_pk_bf16_f32 v7, v46, v47
	v_cvt_pk_bf16_f32 v8, v12, v13
	v_cvt_pk_bf16_f32 v9, v14, v15
	buffer_store_dwordx4 v[6:9], v2, s[24:27], 0 offen sc1
	v_cvt_pk_bf16_f32 v2, v36, v37
	v_cvt_pk_bf16_f32 v3, v38, v39
	v_cvt_pk_bf16_f32 v4, v4, v5
	v_cvt_pk_bf16_f32 v5, v18, v16
	s_nop 1
	v_add_u32_e32 v6, 0xdc000, v97
	buffer_store_dwordx4 v[2:5], v6, s[24:27], 0 offen sc1
	s_nop 1
	v_cvt_pk_bf16_f32 v2, v32, v33
	v_cvt_pk_bf16_f32 v3, v34, v35
	v_cvt_pk_bf16_f32 v4, v0, v1
	v_add_u32_e32 v0, 0xf2000, v97
	v_cvt_pk_bf16_f32 v5, v10, v11
	buffer_store_dwordx4 v[2:5], v0, s[24:27], 0 offen sc1
	s_mov_b64 s[24:25], -1
	s_cbranch_vccnz .LBB0_775
	s_andn2_b64 vcc, exec, s[8:9]
	s_cbranch_vccnz .LBB0_774
	s_barrier
	s_branch .LBB0_774
